# attention-A: extra mask path for tiles wholly inside the +-64 window (3 VALU per score instead of 5) on top of v_stack2
# baseline (speedup 1.0000x reference)
.LBB0_553:
	v_lshlrev_b32_e32 v8, 5, v195
	v_and_b32_e32 v5, 24, v5
	s_movk_i32 s19, 0xe0
	v_and_or_b32 v5, v8, s19, v5
	v_add_u32_e32 v8, 32, v195
	v_lshrrev_b32_e32 v6, 5, v4
	v_lshrrev_b32_e32 v7, 5, v2
	s_mov_b32 s22, 0x7ffffc
	v_lshrrev_b32_e32 v9, 1, v8
	v_and_or_b32 v6, v6, s22, v7
	v_lshlrev_b32_e32 v5, 1, v5
	v_and_or_b32 v7, v9, s22, v7
	v_lshl_or_b32 v6, v6, 9, v5
	v_lshl_or_b32 v5, v7, 9, v5
	v_add_u32_e32 v196, 0, v6
	v_add_u32_e32 v197, 0, v5
	v_lshlrev_b32_e32 v5, 1, v2
	v_lshlrev_b32_e32 v6, 8, v195
	v_and_b32_e32 v7, 0x70, v4
	v_bitop3_b32 v6, v5, v6, v7 bitop3:0xde
	v_add_u32_e32 v198, 0, v6
	v_lshlrev_b32_e32 v6, 8, v8
	v_bitop3_b32 v5, v5, v6, v7 bitop3:0xde
	v_add_u32_e32 v199, 0, v5
	v_add_u32_e32 v5, 0x80, v209
	s_movk_i32 s19, 0xff7f
	v_add_u32_e32 v8, 0xa0, v209
	v_min_i32_e32 v5, s3, v5
	v_cmp_lt_i32_e32 vcc, s19, v209
	s_movk_i32 s19, 0xff5f
	s_waitcnt vmcnt(7)
	ds_write_b128 v196, v[162:165]
	v_cndmask_b32_e32 v6, 0, v5, vcc
	v_min_i32_e32 v5, s3, v8
	v_cmp_lt_i32_e32 vcc, s19, v209
	v_ashrrev_i32_e32 v7, 31, v6
	v_lshlrev_b64 v[6:7], s18, v[6:7]
	v_cndmask_b32_e32 v8, 0, v5, vcc
	v_ashrrev_i32_e32 v9, 31, v8
	v_lshlrev_b64 v[8:9], s18, v[8:9]
	v_lshl_add_u64 v[6:7], v[6:7], 0, v[2:3]
	v_lshl_add_u64 v[8:9], v[8:9], 0, v[2:3]
	v_lshlrev_b64 v[6:7], 1, v[6:7]
	v_lshlrev_b64 v[8:9], 1, v[8:9]
	v_lshl_add_u64 v[10:11], s[12:13], 0, v[6:7]
	v_lshl_add_u64 v[12:13], s[12:13], 0, v[8:9]
	v_lshl_add_u64 v[8:9], s[10:11], 0, v[8:9]
	s_waitcnt vmcnt(6)
	ds_write_b128 v197, v[158:161]
	s_waitcnt vmcnt(5)
	ds_write_b128 v198, v[154:157] offset:32768
	s_waitcnt vmcnt(4)
	ds_write_b128 v199, v[150:153] offset:32768
	s_waitcnt lgkmcnt(0)
	s_barrier
	s_waitcnt vmcnt(0)
	global_load_dwordx4 v[150:153], v[10:11], off
	global_load_dwordx4 v[154:157], v[12:13], off
	v_lshl_add_u64 v[6:7], s[10:11], 0, v[6:7]
	global_load_dwordx4 v[166:169], v[8:9], off
	global_load_dwordx4 v[170:173], v[6:7], off
	s_cmp_lg_u32 0, -1
	s_cselect_b32 s19, 0, 0
	v_cvt_f32_u32_e32 v7, s16
	s_lshl_b32 s16, s31, 1
	s_or_b32 s16, s16, 1
	v_cvt_f32_ubyte0_e32 v8, s16
	v_and_b32_e32 v189, 63, v4
	v_mul_f32_e32 v8, -0.5, v8
	v_lshlrev_b32_e32 v5, 4, v189
	v_exp_f32_e32 v8, v8
	v_lshlrev_b32_e32 v4, 3, v189
	v_and_b32_e32 v5, 0xc0, v5
	v_lshlrev_b32_e32 v6, 1, v189
	v_and_or_b32 v5, v4, 24, v5
	v_and_b32_e32 v6, 32, v6
	v_and_b32_e32 v4, 0x100, v4
	s_and_b32 s16, s17, 0x3fffffc0
	v_or3_b32 v87, v5, v6, v4
	v_mul_f32_e32 v4, 0xbfb8aa3b, v7
	s_lshl_b32 s16, s16, 2
	v_lshlrev_b32_e32 v190, 4, v188
	v_lshlrev_b32_e32 v5, 4, v187
	v_mul_f32_e32 v193, v8, v4
	s_add_i32 s44, s16, 0
	s_ashr_i32 s46, s17, 7
	v_and_b32_e32 v5, 0x70, v5
	v_or_b32_e32 v7, 32, v190
	v_or_b32_e32 v8, 64, v190
	v_or_b32_e32 v9, 0x60, v190
	v_or_b32_e32 v10, 0x80, v190
	v_or_b32_e32 v11, 0xa0, v190
	v_or_b32_e32 v12, 0xc0, v190
	v_or_b32_e32 v13, 0xe0, v190
	v_add_u32_e32 v208, s19, v87
	s_add_i32 s44, s44, 0x10000
	v_lshlrev_b32_e32 v4, 8, v187
	v_xad_u32 v6, v190, v5, 0
	v_xad_u32 v7, v7, v5, 0
	v_xad_u32 v8, v8, v5, 0
	v_xad_u32 v9, v9, v5, 0
	v_xad_u32 v10, v10, v5, 0
	v_xad_u32 v11, v11, v5, 0
	v_xad_u32 v12, v12, v5, 0
	v_xad_u32 v5, v13, v5, 0
	v_lshlrev_b32_e32 v185, 2, v188
	s_add_i32 s19, s46, -1
	v_add_u32_e32 v194, s27, v185
	v_cmp_gt_u32_e64 s[38:39], 32, v189
	v_lshl_add_u32 v191, v187, 2, s44
	s_cmp_lt_u32 s19, -3
	v_add_u32_e32 v207, v6, v4
	v_add_u32_e32 v206, v7, v4
	v_add_u32_e32 v205, v8, v4
	v_add_u32_e32 v204, v9, v4
	v_add_u32_e32 v203, v10, v4
	v_add_u32_e32 v202, v11, v4
	v_add_u32_e32 v201, v12, v4
	v_add_u32_e32 v200, v5, v4
	s_cbranch_scc1 .LBB0_558
	ds_read_b128 v[4:7], v207 offset:32768
	ds_read_b128 v[8:11], v207 offset:40960
	ds_read_b128 v[36:39], v206 offset:32768
	ds_read_b128 v[40:43], v206 offset:40960
	s_waitcnt lgkmcnt(3)
	v_mfma_f32_32x32x16_bf16 v[20:35], v[4:7], v[110:113], 0
	s_waitcnt lgkmcnt(2)
	v_mfma_f32_32x32x16_bf16 v[4:19], v[8:11], v[110:113], 0
	ds_read_b128 v[44:47], v205 offset:32768
	ds_read_b128 v[48:51], v205 offset:40960
	s_waitcnt lgkmcnt(3)
	v_mfma_f32_32x32x16_bf16 v[20:35], v[36:39], v[130:133], v[20:35]
	s_waitcnt lgkmcnt(2)
	v_mfma_f32_32x32x16_bf16 v[4:19], v[40:43], v[130:133], v[4:19]
	ds_read_b128 v[36:39], v204 offset:32768
	ds_read_b128 v[40:43], v204 offset:40960
	s_waitcnt lgkmcnt(3)
	v_mfma_f32_32x32x16_bf16 v[20:35], v[44:47], v[126:129], v[20:35]
	s_waitcnt lgkmcnt(2)
	v_mfma_f32_32x32x16_bf16 v[4:19], v[48:51], v[126:129], v[4:19]
	ds_read_b128 v[44:47], v203 offset:32768
	ds_read_b128 v[48:51], v203 offset:40960
	s_waitcnt lgkmcnt(3)
	v_mfma_f32_32x32x16_bf16 v[20:35], v[36:39], v[122:125], v[20:35]
	s_waitcnt lgkmcnt(2)
	v_mfma_f32_32x32x16_bf16 v[4:19], v[40:43], v[122:125], v[4:19]
	ds_read_b128 v[36:39], v202 offset:32768
	ds_read_b128 v[40:43], v202 offset:40960
	s_waitcnt lgkmcnt(3)
	v_mfma_f32_32x32x16_bf16 v[20:35], v[44:47], v[118:121], v[20:35]
	s_waitcnt lgkmcnt(2)
	v_mfma_f32_32x32x16_bf16 v[4:19], v[48:51], v[118:121], v[4:19]
	ds_read_b128 v[44:47], v201 offset:32768
	ds_read_b128 v[48:51], v201 offset:40960
	s_waitcnt lgkmcnt(3)
	v_mfma_f32_32x32x16_bf16 v[20:35], v[36:39], v[114:117], v[20:35]
	s_waitcnt lgkmcnt(2)
	v_mfma_f32_32x32x16_bf16 v[4:19], v[40:43], v[114:117], v[4:19]
	ds_read_b128 v[36:39], v200 offset:32768
	ds_read_b128 v[40:43], v200 offset:40960
	s_waitcnt lgkmcnt(3)
	v_mfma_f32_32x32x16_bf16 v[20:35], v[44:47], v[106:109], v[20:35]
	s_waitcnt lgkmcnt(2)
	v_mfma_f32_32x32x16_bf16 v[4:19], v[48:51], v[106:109], v[4:19]
	s_waitcnt lgkmcnt(1)
	v_mfma_f32_32x32x16_bf16 v[20:35], v[36:39], v[102:105], v[20:35]
	s_waitcnt lgkmcnt(0)
	v_mfma_f32_32x32x16_bf16 v[4:19], v[40:43], v[102:105], v[4:19]
	v_sub_u32_e32 v36, v192, v194
	v_readfirstlane_b32 s100, v36
	v_cvt_f32_i32_e32 v36, v36
	v_readfirstlane_b32 s40, v194
	s_add_i32 s41, s40, 64
	s_cmp_lt_i32 s40, 0
	s_cbranch_scc1 .Lam_out_0
	s_cmp_gt_i32 s41, s45
	s_cbranch_scc1 .Lam_out_0
	s_add_i32 s100, s100, 1
	s_cmp_lt_u32 s100, 35
	s_cbranch_scc1 .Lam_in_0
	v_add_f32_e32 v37, 0xc2000000, v36
	v_mov_b32_e32 v38, v36
	v_cmp_le_f32_e64 vcc, |v37|, s76
	v_cmp_le_f32_e64 s[16:17], |v38|, s76
	v_mul_f32_e64 v37, v193, |v37|
	v_mul_f32_e64 v38, v193, |v38|
	v_fmac_f32_e32 v37, 0x3e0293ee, v4
	v_fmac_f32_e32 v38, 0x3e0293ee, v20
	v_cndmask_b32_e32 v4, v234, v37, vcc
	v_cndmask_b32_e64 v20, v234, v38, s[16:17]
	v_add_f32_e32 v37, -1.0, v36
	v_add_f32_e32 v38, 0xc2040000, v36
	v_cmp_le_f32_e64 vcc, |v37|, s76
	v_cmp_le_f32_e64 s[16:17], |v38|, s76
	v_mul_f32_e64 v37, v193, |v37|
	v_mul_f32_e64 v38, v193, |v38|
	v_fmac_f32_e32 v37, 0x3e0293ee, v21
	v_fmac_f32_e32 v38, 0x3e0293ee, v5
	v_cndmask_b32_e32 v21, v234, v37, vcc
	v_cndmask_b32_e64 v5, v234, v38, s[16:17]
	v_add_f32_e32 v37, -2.0, v36
	v_add_f32_e32 v38, 0xc2080000, v36
	v_cmp_le_f32_e64 vcc, |v37|, s76
	v_cmp_le_f32_e64 s[16:17], |v38|, s76
	v_mul_f32_e64 v37, v193, |v37|
	v_mul_f32_e64 v38, v193, |v38|
	v_fmac_f32_e32 v37, 0x3e0293ee, v22
	v_fmac_f32_e32 v38, 0x3e0293ee, v6
	v_cndmask_b32_e32 v22, v234, v37, vcc
	v_cndmask_b32_e64 v6, v234, v38, s[16:17]
	v_add_f32_e32 v37, 0xc0400000, v36
	v_add_f32_e32 v38, 0xc20c0000, v36
	v_cmp_le_f32_e64 vcc, |v37|, s76
	v_cmp_le_f32_e64 s[16:17], |v38|, s76
	v_mul_f32_e64 v37, v193, |v37|
	v_mul_f32_e64 v38, v193, |v38|
	v_fmac_f32_e32 v37, 0x3e0293ee, v23
	v_fmac_f32_e32 v38, 0x3e0293ee, v7
	v_cndmask_b32_e32 v23, v234, v37, vcc
	v_cndmask_b32_e64 v7, v234, v38, s[16:17]
	v_add_f32_e32 v37, 0xc1000000, v36
	v_add_f32_e32 v38, 0xc2200000, v36
	v_cmp_le_f32_e64 vcc, |v37|, s76
	v_cmp_le_f32_e64 s[16:17], |v38|, s76
	v_mul_f32_e64 v37, v193, |v37|
	v_mul_f32_e64 v38, v193, |v38|
	v_fmac_f32_e32 v37, 0x3e0293ee, v24
	v_fmac_f32_e32 v38, 0x3e0293ee, v8
	v_cndmask_b32_e32 v24, v234, v37, vcc
	v_cndmask_b32_e64 v8, v234, v38, s[16:17]
	v_add_f32_e32 v37, 0xc1100000, v36
	v_add_f32_e32 v38, 0xc2240000, v36
	v_cmp_le_f32_e64 vcc, |v37|, s76
	v_cmp_le_f32_e64 s[16:17], |v38|, s76
	v_mul_f32_e64 v37, v193, |v37|
	v_mul_f32_e64 v38, v193, |v38|
	v_fmac_f32_e32 v37, 0x3e0293ee, v25
	v_fmac_f32_e32 v38, 0x3e0293ee, v9
	v_cndmask_b32_e32 v25, v234, v37, vcc
	v_cndmask_b32_e64 v9, v234, v38, s[16:17]
	v_add_f32_e32 v37, 0xc1200000, v36
	v_add_f32_e32 v38, 0xc2280000, v36
	v_cmp_le_f32_e64 vcc, |v37|, s76
	v_cmp_le_f32_e64 s[16:17], |v38|, s76
	v_mul_f32_e64 v37, v193, |v37|
	v_mul_f32_e64 v38, v193, |v38|
	v_fmac_f32_e32 v37, 0x3e0293ee, v26
	v_fmac_f32_e32 v38, 0x3e0293ee, v10
	v_cndmask_b32_e32 v26, v234, v37, vcc
	v_cndmask_b32_e64 v10, v234, v38, s[16:17]
	v_add_f32_e32 v37, 0xc1300000, v36
	v_add_f32_e32 v38, 0xc22c0000, v36
	v_cmp_le_f32_e64 vcc, |v37|, s76
	v_cmp_le_f32_e64 s[16:17], |v38|, s76
	v_mul_f32_e64 v37, v193, |v37|
	v_mul_f32_e64 v38, v193, |v38|
	v_fmac_f32_e32 v37, 0x3e0293ee, v27
	v_fmac_f32_e32 v38, 0x3e0293ee, v11
	v_cndmask_b32_e32 v27, v234, v37, vcc
	v_cndmask_b32_e64 v11, v234, v38, s[16:17]
	v_add_f32_e32 v37, 0xc1800000, v36
	v_add_f32_e32 v38, 0xc2400000, v36
	v_cmp_le_f32_e64 vcc, |v37|, s76
	v_cmp_le_f32_e64 s[16:17], |v38|, s76
	v_mul_f32_e64 v37, v193, |v37|
	v_mul_f32_e64 v38, v193, |v38|
	v_fmac_f32_e32 v37, 0x3e0293ee, v28
	v_fmac_f32_e32 v38, 0x3e0293ee, v12
	v_cndmask_b32_e32 v28, v234, v37, vcc
	v_cndmask_b32_e64 v12, v234, v38, s[16:17]
	v_add_f32_e32 v37, 0xc1880000, v36
	v_add_f32_e32 v38, 0xc2440000, v36
	v_cmp_le_f32_e64 vcc, |v37|, s76
	v_cmp_le_f32_e64 s[16:17], |v38|, s76
	v_mul_f32_e64 v37, v193, |v37|
	v_mul_f32_e64 v38, v193, |v38|
	v_fmac_f32_e32 v37, 0x3e0293ee, v29
	v_fmac_f32_e32 v38, 0x3e0293ee, v13
	v_cndmask_b32_e32 v29, v234, v37, vcc
	v_cndmask_b32_e64 v13, v234, v38, s[16:17]
	v_add_f32_e32 v37, 0xc1900000, v36
	v_add_f32_e32 v38, 0xc2480000, v36
	v_cmp_le_f32_e64 vcc, |v37|, s76
	v_cmp_le_f32_e64 s[16:17], |v38|, s76
	v_mul_f32_e64 v37, v193, |v37|
	v_mul_f32_e64 v38, v193, |v38|
	v_fmac_f32_e32 v37, 0x3e0293ee, v30
	v_fmac_f32_e32 v38, 0x3e0293ee, v14
	v_cndmask_b32_e32 v30, v234, v37, vcc
	v_cndmask_b32_e64 v14, v234, v38, s[16:17]
	v_add_f32_e32 v37, 0xc1980000, v36
	v_add_f32_e32 v38, 0xc24c0000, v36
	v_cmp_le_f32_e64 vcc, |v37|, s76
	v_cmp_le_f32_e64 s[16:17], |v38|, s76
	v_mul_f32_e64 v37, v193, |v37|
	v_mul_f32_e64 v38, v193, |v38|
	v_fmac_f32_e32 v37, 0x3e0293ee, v31
	v_fmac_f32_e32 v38, 0x3e0293ee, v15
	v_cndmask_b32_e32 v31, v234, v37, vcc
	v_cndmask_b32_e64 v15, v234, v38, s[16:17]
	v_add_f32_e32 v37, 0xc1c00000, v36
	v_add_f32_e32 v38, 0xc2600000, v36
	v_cmp_le_f32_e64 vcc, |v37|, s76
	v_cmp_le_f32_e64 s[16:17], |v38|, s76
	v_mul_f32_e64 v37, v193, |v37|
	v_mul_f32_e64 v38, v193, |v38|
	v_fmac_f32_e32 v37, 0x3e0293ee, v32
	v_fmac_f32_e32 v38, 0x3e0293ee, v16
	v_cndmask_b32_e32 v32, v234, v37, vcc
	v_cndmask_b32_e64 v16, v234, v38, s[16:17]
	v_add_f32_e32 v37, 0xc1c80000, v36
	v_add_f32_e32 v38, 0xc2640000, v36
	v_cmp_le_f32_e64 vcc, |v37|, s76
	v_cmp_le_f32_e64 s[16:17], |v38|, s76
	v_mul_f32_e64 v37, v193, |v37|
	v_mul_f32_e64 v38, v193, |v38|
	v_fmac_f32_e32 v37, 0x3e0293ee, v33
	v_fmac_f32_e32 v38, 0x3e0293ee, v17
	v_cndmask_b32_e32 v33, v234, v37, vcc
	v_cndmask_b32_e64 v17, v234, v38, s[16:17]
	v_add_f32_e32 v37, 0xc1d00000, v36
	v_add_f32_e32 v38, 0xc2680000, v36
	v_cmp_le_f32_e64 vcc, |v37|, s76
	v_cmp_le_f32_e64 s[16:17], |v38|, s76
	v_mul_f32_e64 v37, v193, |v37|
	v_mul_f32_e64 v38, v193, |v38|
	v_fmac_f32_e32 v37, 0x3e0293ee, v34
	v_fmac_f32_e32 v38, 0x3e0293ee, v18
	v_cndmask_b32_e32 v34, v234, v37, vcc
	v_cndmask_b32_e64 v18, v234, v38, s[16:17]
	v_add_f32_e32 v37, 0xc26c0000, v36
	v_add_f32_e32 v38, 0xc1d80000, v36
	v_cmp_le_f32_e64 vcc, |v37|, s76
	v_cmp_le_f32_e64 s[16:17], |v38|, s76
	v_mul_f32_e64 v37, v193, |v37|
	v_mul_f32_e64 v38, v193, |v38|
	v_fmac_f32_e32 v37, 0x3e0293ee, v19
	v_fmac_f32_e32 v38, 0x3e0293ee, v35
	v_cndmask_b32_e32 v19, v234, v37, vcc
	v_cndmask_b32_e64 v35, v234, v38, s[16:17]
	s_branch .Lam_done_0
.Lam_in_0:
	s_mov_b32 s101, 0x3e0293ee
	s_nop 3
	v_add_f32_e32 v37, 0xc2000000, v36
	v_mul_f32_e64 v37, v193, |v37|
	v_mul_f32_e64 v38, v193, |v36|
	v_fma_f32 v4, s101, v4, v37
	v_fma_f32 v20, s101, v20, v38
	v_add_f32_e32 v37, -1.0, v36
	v_add_f32_e32 v38, 0xc2040000, v36
	v_mul_f32_e64 v37, v193, |v37|
	v_mul_f32_e64 v38, v193, |v38|
	v_fma_f32 v21, s101, v21, v37
	v_fma_f32 v5, s101, v5, v38
	v_add_f32_e32 v37, -2.0, v36
	v_add_f32_e32 v38, 0xc2080000, v36
	v_mul_f32_e64 v37, v193, |v37|
	v_mul_f32_e64 v38, v193, |v38|
	v_fma_f32 v22, s101, v22, v37
	v_fma_f32 v6, s101, v6, v38
	v_add_f32_e32 v37, 0xc0400000, v36
	v_add_f32_e32 v38, 0xc20c0000, v36
	v_mul_f32_e64 v37, v193, |v37|
	v_mul_f32_e64 v38, v193, |v38|
	v_fma_f32 v23, s101, v23, v37
	v_fma_f32 v7, s101, v7, v38
	v_add_f32_e32 v37, 0xc1000000, v36
	v_add_f32_e32 v38, 0xc2200000, v36
	v_mul_f32_e64 v37, v193, |v37|
	v_mul_f32_e64 v38, v193, |v38|
	v_fma_f32 v24, s101, v24, v37
	v_fma_f32 v8, s101, v8, v38
	v_add_f32_e32 v37, 0xc1100000, v36
	v_add_f32_e32 v38, 0xc2240000, v36
	v_mul_f32_e64 v37, v193, |v37|
	v_mul_f32_e64 v38, v193, |v38|
	v_fma_f32 v25, s101, v25, v37
	v_fma_f32 v9, s101, v9, v38
	v_add_f32_e32 v37, 0xc1200000, v36
	v_add_f32_e32 v38, 0xc2280000, v36
	v_mul_f32_e64 v37, v193, |v37|
	v_mul_f32_e64 v38, v193, |v38|
	v_fma_f32 v26, s101, v26, v37
	v_fma_f32 v10, s101, v10, v38
	v_add_f32_e32 v37, 0xc1300000, v36
	v_add_f32_e32 v38, 0xc22c0000, v36
	v_mul_f32_e64 v37, v193, |v37|
	v_mul_f32_e64 v38, v193, |v38|
	v_fma_f32 v27, s101, v27, v37
	v_fma_f32 v11, s101, v11, v38
	v_add_f32_e32 v37, 0xc1800000, v36
	v_add_f32_e32 v38, 0xc2400000, v36
	v_mul_f32_e64 v37, v193, |v37|
	v_mul_f32_e64 v38, v193, |v38|
	v_fma_f32 v28, s101, v28, v37
	v_fma_f32 v12, s101, v12, v38
	v_add_f32_e32 v37, 0xc1880000, v36
	v_add_f32_e32 v38, 0xc2440000, v36
	v_mul_f32_e64 v37, v193, |v37|
	v_mul_f32_e64 v38, v193, |v38|
	v_fma_f32 v29, s101, v29, v37
	v_fma_f32 v13, s101, v13, v38
	v_add_f32_e32 v37, 0xc1900000, v36
	v_add_f32_e32 v38, 0xc2480000, v36
	v_mul_f32_e64 v37, v193, |v37|
	v_mul_f32_e64 v38, v193, |v38|
	v_fma_f32 v30, s101, v30, v37
	v_fma_f32 v14, s101, v14, v38
	v_add_f32_e32 v37, 0xc1980000, v36
	v_add_f32_e32 v38, 0xc24c0000, v36
	v_mul_f32_e64 v37, v193, |v37|
	v_mul_f32_e64 v38, v193, |v38|
	v_fma_f32 v31, s101, v31, v37
	v_fma_f32 v15, s101, v15, v38
	v_add_f32_e32 v37, 0xc1c00000, v36
	v_add_f32_e32 v38, 0xc2600000, v36
	v_mul_f32_e64 v37, v193, |v37|
	v_mul_f32_e64 v38, v193, |v38|
	v_fma_f32 v32, s101, v32, v37
	v_fma_f32 v16, s101, v16, v38
	v_add_f32_e32 v37, 0xc1c80000, v36
	v_add_f32_e32 v38, 0xc2640000, v36
	v_mul_f32_e64 v37, v193, |v37|
	v_mul_f32_e64 v38, v193, |v38|
	v_fma_f32 v33, s101, v33, v37
	v_fma_f32 v17, s101, v17, v38
	v_add_f32_e32 v37, 0xc1d00000, v36
	v_add_f32_e32 v38, 0xc2680000, v36
	v_mul_f32_e64 v37, v193, |v37|
	v_mul_f32_e64 v38, v193, |v38|
	v_fma_f32 v34, s101, v34, v37
	v_fma_f32 v18, s101, v18, v38
	v_add_f32_e32 v37, 0xc26c0000, v36
	v_add_f32_e32 v38, 0xc1d80000, v36
	v_mul_f32_e64 v37, v193, |v37|
	v_mul_f32_e64 v38, v193, |v38|
	v_fma_f32 v19, s101, v19, v37
	v_fma_f32 v35, s101, v35, v38
	s_branch .Lam_done_0

.LBB0_561:
	v_add_u32_e32 v210, 0x80, v86
	v_add_u32_e32 v69, 0xa0, v86
	v_min_i32_e32 v70, s3, v210
	v_cmp_lt_i32_e32 vcc, -1, v210
	s_movk_i32 s16, 0xffdf
	v_min_i32_e32 v69, s3, v69
	v_cndmask_b32_e32 v70, 0, v70, vcc
	v_cmp_lt_i32_e32 vcc, s16, v210
	v_ashrrev_i32_e32 v71, 31, v70
	v_lshlrev_b64 v[70:71], s18, v[70:71]
	v_cndmask_b32_e32 v72, 0, v69, vcc
	v_ashrrev_i32_e32 v73, 31, v72
	v_lshlrev_b64 v[72:73], s18, v[72:73]
	v_lshl_add_u64 v[70:71], v[70:71], 0, v[2:3]
	v_lshl_add_u64 v[72:73], v[72:73], 0, v[2:3]
	v_lshlrev_b64 v[70:71], 1, v[70:71]
	v_lshlrev_b64 v[72:73], 1, v[72:73]
	v_lshl_add_u64 v[74:75], s[12:13], 0, v[70:71]
	v_lshl_add_u64 v[76:77], s[12:13], 0, v[72:73]
	v_lshl_add_u64 v[72:73], s[10:11], 0, v[72:73]
	s_waitcnt vmcnt(4)
	ds_write_b128 v196, v[134:137] offset:16384
	ds_write_b128 v197, v[138:141] offset:16384
	ds_write_b128 v198, v[142:145] offset:49152
	ds_write_b128 v199, v[146:149] offset:49152
	s_waitcnt lgkmcnt(0)
	s_barrier
	global_load_dwordx4 v[142:145], v[74:75], off
	global_load_dwordx4 v[146:149], v[76:77], off
	v_lshl_add_u64 v[70:71], s[10:11], 0, v[70:71]
	global_load_dwordx4 v[158:161], v[72:73], off
	global_load_dwordx4 v[162:165], v[70:71], off
	s_cmp_lg_u32 0, -1
	s_cselect_b32 s16, 0, 0
	s_addk_i32 s16, 0x4000
	s_add_i32 s17, s46, 1
	s_cmp_gt_u32 s17, 2
	v_add_u32_e32 v69, s16, v87
	s_cbranch_scc1 .LBB0_567
	ds_read_b128 v[70:73], v207 offset:49152
	ds_read_b128 v[74:77], v207 offset:57344
	ds_read_b128 v[134:137], v206 offset:49152
	ds_read_b128 v[138:141], v206 offset:57344
	s_waitcnt lgkmcnt(3)
	v_mfma_f32_32x32x16_bf16 v[86:101], v[70:73], v[110:113], 0
	s_waitcnt lgkmcnt(2)
	v_mfma_f32_32x32x16_bf16 v[70:85], v[74:77], v[110:113], 0
	ds_read_b128 v[214:217], v205 offset:49152
	ds_read_b128 v[218:221], v205 offset:57344
	s_waitcnt lgkmcnt(3)
	v_mfma_f32_32x32x16_bf16 v[86:101], v[134:137], v[130:133], v[86:101]
	s_waitcnt lgkmcnt(2)
	v_mfma_f32_32x32x16_bf16 v[70:85], v[138:141], v[130:133], v[70:85]
	ds_read_b128 v[134:137], v204 offset:49152
	ds_read_b128 v[138:141], v204 offset:57344
	s_waitcnt lgkmcnt(3)
	v_mfma_f32_32x32x16_bf16 v[86:101], v[214:217], v[126:129], v[86:101]
	s_waitcnt lgkmcnt(2)
	v_mfma_f32_32x32x16_bf16 v[70:85], v[218:221], v[126:129], v[70:85]
	ds_read_b128 v[214:217], v203 offset:49152
	ds_read_b128 v[218:221], v203 offset:57344
	s_waitcnt lgkmcnt(3)
	v_mfma_f32_32x32x16_bf16 v[86:101], v[134:137], v[122:125], v[86:101]
	s_waitcnt lgkmcnt(2)
	v_mfma_f32_32x32x16_bf16 v[70:85], v[138:141], v[122:125], v[70:85]
	ds_read_b128 v[134:137], v202 offset:49152
	ds_read_b128 v[138:141], v202 offset:57344
	s_waitcnt lgkmcnt(3)
	v_mfma_f32_32x32x16_bf16 v[86:101], v[214:217], v[118:121], v[86:101]
	s_waitcnt lgkmcnt(2)
	v_mfma_f32_32x32x16_bf16 v[70:85], v[218:221], v[118:121], v[70:85]
	ds_read_b128 v[214:217], v201 offset:49152
	ds_read_b128 v[218:221], v201 offset:57344
	s_waitcnt lgkmcnt(3)
	v_mfma_f32_32x32x16_bf16 v[86:101], v[134:137], v[114:117], v[86:101]
	s_waitcnt lgkmcnt(2)
	v_mfma_f32_32x32x16_bf16 v[70:85], v[138:141], v[114:117], v[70:85]
	ds_read_b128 v[134:137], v200 offset:49152
	ds_read_b128 v[138:141], v200 offset:57344
	s_waitcnt lgkmcnt(3)
	v_mfma_f32_32x32x16_bf16 v[86:101], v[214:217], v[106:109], v[86:101]
	s_waitcnt lgkmcnt(2)
	v_mfma_f32_32x32x16_bf16 v[70:85], v[218:221], v[106:109], v[70:85]
	s_waitcnt lgkmcnt(1)
	v_mfma_f32_32x32x16_bf16 v[86:101], v[134:137], v[102:105], v[86:101]
	s_waitcnt lgkmcnt(0)
	v_mfma_f32_32x32x16_bf16 v[70:85], v[138:141], v[102:105], v[70:85]
	v_add_u32_e32 v134, 64, v194
	v_sub_u32_e32 v135, v192, v134
	v_readfirstlane_b32 s100, v135
	v_cvt_f32_i32_e32 v135, v135
	v_readfirstlane_b32 s40, v134
	s_add_i32 s41, s40, 64
	s_cmp_lt_i32 s40, 0
	s_cbranch_scc1 .Lam_out_1
	s_cmp_gt_i32 s41, s45
	s_cbranch_scc1 .Lam_out_1
	s_add_i32 s100, s100, 1
	s_cmp_lt_u32 s100, 35
	s_cbranch_scc1 .Lam_in_1
	v_mov_b32_e32 v134, v135
	v_add_f32_e32 v136, 0xc2000000, v135
	v_cmp_le_f32_e64 vcc, |v134|, s76
	v_cmp_le_f32_e64 s[16:17], |v136|, s76
	v_mul_f32_e64 v134, v193, |v134|
	v_mul_f32_e64 v136, v193, |v136|
	v_fmac_f32_e32 v134, 0x3e0293ee, v86
	v_fmac_f32_e32 v136, 0x3e0293ee, v70
	v_cndmask_b32_e32 v86, v234, v134, vcc
	v_cndmask_b32_e64 v70, v234, v136, s[16:17]
	v_add_f32_e32 v134, -1.0, v135
	v_add_f32_e32 v136, 0xc2040000, v135
	v_cmp_le_f32_e64 vcc, |v134|, s76
	v_cmp_le_f32_e64 s[16:17], |v136|, s76
	v_mul_f32_e64 v134, v193, |v134|
	v_mul_f32_e64 v136, v193, |v136|
	v_fmac_f32_e32 v134, 0x3e0293ee, v87
	v_fmac_f32_e32 v136, 0x3e0293ee, v71
	v_cndmask_b32_e32 v87, v234, v134, vcc
	v_cndmask_b32_e64 v71, v234, v136, s[16:17]
	v_add_f32_e32 v134, -2.0, v135
	v_add_f32_e32 v136, 0xc2080000, v135
	v_cmp_le_f32_e64 vcc, |v134|, s76
	v_cmp_le_f32_e64 s[16:17], |v136|, s76
	v_mul_f32_e64 v134, v193, |v134|
	v_mul_f32_e64 v136, v193, |v136|
	v_fmac_f32_e32 v134, 0x3e0293ee, v88
	v_fmac_f32_e32 v136, 0x3e0293ee, v72
	v_cndmask_b32_e32 v88, v234, v134, vcc
	v_cndmask_b32_e64 v72, v234, v136, s[16:17]
	v_add_f32_e32 v134, 0xc0400000, v135
	v_add_f32_e32 v136, 0xc20c0000, v135
	v_cmp_le_f32_e64 vcc, |v134|, s76
	v_cmp_le_f32_e64 s[16:17], |v136|, s76
	v_mul_f32_e64 v134, v193, |v134|
	v_mul_f32_e64 v136, v193, |v136|
	v_fmac_f32_e32 v134, 0x3e0293ee, v89
	v_fmac_f32_e32 v136, 0x3e0293ee, v73
	v_cndmask_b32_e32 v89, v234, v134, vcc
	v_cndmask_b32_e64 v73, v234, v136, s[16:17]
	v_add_f32_e32 v134, 0xc1000000, v135
	v_add_f32_e32 v136, 0xc2200000, v135
	v_cmp_le_f32_e64 vcc, |v134|, s76
	v_cmp_le_f32_e64 s[16:17], |v136|, s76
	v_mul_f32_e64 v134, v193, |v134|
	v_mul_f32_e64 v136, v193, |v136|
	v_fmac_f32_e32 v134, 0x3e0293ee, v90
	v_fmac_f32_e32 v136, 0x3e0293ee, v74
	v_cndmask_b32_e32 v90, v234, v134, vcc
	v_cndmask_b32_e64 v74, v234, v136, s[16:17]
	v_add_f32_e32 v134, 0xc1100000, v135
	v_add_f32_e32 v136, 0xc2240000, v135
	v_cmp_le_f32_e64 vcc, |v134|, s76
	v_cmp_le_f32_e64 s[16:17], |v136|, s76
	v_mul_f32_e64 v134, v193, |v134|
	v_mul_f32_e64 v136, v193, |v136|
	v_fmac_f32_e32 v134, 0x3e0293ee, v91
	v_fmac_f32_e32 v136, 0x3e0293ee, v75
	v_cndmask_b32_e32 v91, v234, v134, vcc
	v_cndmask_b32_e64 v75, v234, v136, s[16:17]
	v_add_f32_e32 v134, 0xc1200000, v135
	v_add_f32_e32 v136, 0xc2280000, v135
	v_cmp_le_f32_e64 vcc, |v134|, s76
	v_cmp_le_f32_e64 s[16:17], |v136|, s76
	v_mul_f32_e64 v134, v193, |v134|
	v_mul_f32_e64 v136, v193, |v136|
	v_fmac_f32_e32 v134, 0x3e0293ee, v92
	v_fmac_f32_e32 v136, 0x3e0293ee, v76
	v_cndmask_b32_e32 v92, v234, v134, vcc
	v_cndmask_b32_e64 v76, v234, v136, s[16:17]
	v_add_f32_e32 v134, 0xc1300000, v135
	v_add_f32_e32 v136, 0xc22c0000, v135
	v_cmp_le_f32_e64 vcc, |v134|, s76
	v_cmp_le_f32_e64 s[16:17], |v136|, s76
	v_mul_f32_e64 v134, v193, |v134|
	v_mul_f32_e64 v136, v193, |v136|
	v_fmac_f32_e32 v134, 0x3e0293ee, v93
	v_fmac_f32_e32 v136, 0x3e0293ee, v77
	v_cndmask_b32_e32 v93, v234, v134, vcc
	v_cndmask_b32_e64 v77, v234, v136, s[16:17]
	v_add_f32_e32 v134, 0xc1800000, v135
	v_add_f32_e32 v136, 0xc2400000, v135
	v_cmp_le_f32_e64 vcc, |v134|, s76
	v_cmp_le_f32_e64 s[16:17], |v136|, s76
	v_mul_f32_e64 v134, v193, |v134|
	v_mul_f32_e64 v136, v193, |v136|
	v_fmac_f32_e32 v134, 0x3e0293ee, v94
	v_fmac_f32_e32 v136, 0x3e0293ee, v78
	v_cndmask_b32_e32 v94, v234, v134, vcc
	v_cndmask_b32_e64 v78, v234, v136, s[16:17]
	v_add_f32_e32 v134, 0xc1880000, v135
	v_add_f32_e32 v136, 0xc2440000, v135
	v_cmp_le_f32_e64 vcc, |v134|, s76
	v_cmp_le_f32_e64 s[16:17], |v136|, s76
	v_mul_f32_e64 v134, v193, |v134|
	v_mul_f32_e64 v136, v193, |v136|
	v_fmac_f32_e32 v134, 0x3e0293ee, v95
	v_fmac_f32_e32 v136, 0x3e0293ee, v79
	v_cndmask_b32_e32 v95, v234, v134, vcc
	v_cndmask_b32_e64 v79, v234, v136, s[16:17]
	v_add_f32_e32 v134, 0xc1900000, v135
	v_add_f32_e32 v136, 0xc2480000, v135
	v_cmp_le_f32_e64 vcc, |v134|, s76
	v_cmp_le_f32_e64 s[16:17], |v136|, s76
	v_mul_f32_e64 v134, v193, |v134|
	v_mul_f32_e64 v136, v193, |v136|
	v_fmac_f32_e32 v134, 0x3e0293ee, v96
	v_fmac_f32_e32 v136, 0x3e0293ee, v80
	v_cndmask_b32_e32 v96, v234, v134, vcc
	v_cndmask_b32_e64 v80, v234, v136, s[16:17]
	v_add_f32_e32 v134, 0xc1980000, v135
	v_add_f32_e32 v136, 0xc24c0000, v135
	v_cmp_le_f32_e64 vcc, |v134|, s76
	v_cmp_le_f32_e64 s[16:17], |v136|, s76
	v_mul_f32_e64 v134, v193, |v134|
	v_mul_f32_e64 v136, v193, |v136|
	v_fmac_f32_e32 v134, 0x3e0293ee, v97
	v_fmac_f32_e32 v136, 0x3e0293ee, v81
	v_cndmask_b32_e32 v97, v234, v134, vcc
	v_cndmask_b32_e64 v81, v234, v136, s[16:17]
	v_add_f32_e32 v134, 0xc1c00000, v135
	v_add_f32_e32 v136, 0xc2600000, v135
	v_cmp_le_f32_e64 vcc, |v134|, s76
	v_cmp_le_f32_e64 s[16:17], |v136|, s76
	v_mul_f32_e64 v134, v193, |v134|
	v_mul_f32_e64 v136, v193, |v136|
	v_fmac_f32_e32 v134, 0x3e0293ee, v98
	v_fmac_f32_e32 v136, 0x3e0293ee, v82
	v_cndmask_b32_e32 v98, v234, v134, vcc
	v_cndmask_b32_e64 v82, v234, v136, s[16:17]
	v_add_f32_e32 v134, 0xc1c80000, v135
	v_add_f32_e32 v136, 0xc2640000, v135
	v_cmp_le_f32_e64 vcc, |v134|, s76
	v_cmp_le_f32_e64 s[16:17], |v136|, s76
	v_mul_f32_e64 v134, v193, |v134|
	v_mul_f32_e64 v136, v193, |v136|
	v_fmac_f32_e32 v134, 0x3e0293ee, v99
	v_fmac_f32_e32 v136, 0x3e0293ee, v83
	v_cndmask_b32_e32 v99, v234, v134, vcc
	v_cndmask_b32_e64 v83, v234, v136, s[16:17]
	v_add_f32_e32 v134, 0xc1d00000, v135
	v_add_f32_e32 v136, 0xc2680000, v135
	v_cmp_le_f32_e64 vcc, |v134|, s76
	v_cmp_le_f32_e64 s[16:17], |v136|, s76
	v_mul_f32_e64 v134, v193, |v134|
	v_mul_f32_e64 v136, v193, |v136|
	v_fmac_f32_e32 v134, 0x3e0293ee, v100
	v_fmac_f32_e32 v136, 0x3e0293ee, v84
	v_cndmask_b32_e32 v100, v234, v134, vcc
	v_cndmask_b32_e64 v84, v234, v136, s[16:17]
	v_add_f32_e32 v134, 0xc1d80000, v135
	v_add_f32_e32 v136, 0xc26c0000, v135
	v_cmp_le_f32_e64 vcc, |v134|, s76
	v_cmp_le_f32_e64 s[16:17], |v136|, s76
	v_mul_f32_e64 v134, v193, |v134|
	v_mul_f32_e64 v136, v193, |v136|
	v_fmac_f32_e32 v134, 0x3e0293ee, v101
	v_fmac_f32_e32 v136, 0x3e0293ee, v85
	v_cndmask_b32_e32 v101, v234, v134, vcc
	v_cndmask_b32_e64 v85, v234, v136, s[16:17]
	s_branch .Lam_done_1
.Lam_in_1:
	s_mov_b32 s101, 0x3e0293ee
	s_nop 3
	v_add_f32_e32 v136, 0xc2000000, v135
	v_mul_f32_e64 v134, v193, |v135|
	v_mul_f32_e64 v136, v193, |v136|
	v_fma_f32 v86, s101, v86, v134
	v_fma_f32 v70, s101, v70, v136
	v_add_f32_e32 v134, -1.0, v135
	v_add_f32_e32 v136, 0xc2040000, v135
	v_mul_f32_e64 v134, v193, |v134|
	v_mul_f32_e64 v136, v193, |v136|
	v_fma_f32 v87, s101, v87, v134
	v_fma_f32 v71, s101, v71, v136
	v_add_f32_e32 v134, -2.0, v135
	v_add_f32_e32 v136, 0xc2080000, v135
	v_mul_f32_e64 v134, v193, |v134|
	v_mul_f32_e64 v136, v193, |v136|
	v_fma_f32 v88, s101, v88, v134
	v_fma_f32 v72, s101, v72, v136
	v_add_f32_e32 v134, 0xc0400000, v135
	v_add_f32_e32 v136, 0xc20c0000, v135
	v_mul_f32_e64 v134, v193, |v134|
	v_mul_f32_e64 v136, v193, |v136|
	v_fma_f32 v89, s101, v89, v134
	v_fma_f32 v73, s101, v73, v136
	v_add_f32_e32 v134, 0xc1000000, v135
	v_add_f32_e32 v136, 0xc2200000, v135
	v_mul_f32_e64 v134, v193, |v134|
	v_mul_f32_e64 v136, v193, |v136|
	v_fma_f32 v90, s101, v90, v134
	v_fma_f32 v74, s101, v74, v136
	v_add_f32_e32 v134, 0xc1100000, v135
	v_add_f32_e32 v136, 0xc2240000, v135
	v_mul_f32_e64 v134, v193, |v134|
	v_mul_f32_e64 v136, v193, |v136|
	v_fma_f32 v91, s101, v91, v134
	v_fma_f32 v75, s101, v75, v136
	v_add_f32_e32 v134, 0xc1200000, v135
	v_add_f32_e32 v136, 0xc2280000, v135
	v_mul_f32_e64 v134, v193, |v134|
	v_mul_f32_e64 v136, v193, |v136|
	v_fma_f32 v92, s101, v92, v134
	v_fma_f32 v76, s101, v76, v136
	v_add_f32_e32 v134, 0xc1300000, v135
	v_add_f32_e32 v136, 0xc22c0000, v135
	v_mul_f32_e64 v134, v193, |v134|
	v_mul_f32_e64 v136, v193, |v136|
	v_fma_f32 v93, s101, v93, v134
	v_fma_f32 v77, s101, v77, v136
	v_add_f32_e32 v134, 0xc1800000, v135
	v_add_f32_e32 v136, 0xc2400000, v135
	v_mul_f32_e64 v134, v193, |v134|
	v_mul_f32_e64 v136, v193, |v136|
	v_fma_f32 v94, s101, v94, v134
	v_fma_f32 v78, s101, v78, v136
	v_add_f32_e32 v134, 0xc1880000, v135
	v_add_f32_e32 v136, 0xc2440000, v135
	v_mul_f32_e64 v134, v193, |v134|
	v_mul_f32_e64 v136, v193, |v136|
	v_fma_f32 v95, s101, v95, v134
	v_fma_f32 v79, s101, v79, v136
	v_add_f32_e32 v134, 0xc1900000, v135
	v_add_f32_e32 v136, 0xc2480000, v135
	v_mul_f32_e64 v134, v193, |v134|
	v_mul_f32_e64 v136, v193, |v136|
	v_fma_f32 v96, s101, v96, v134
	v_fma_f32 v80, s101, v80, v136
	v_add_f32_e32 v134, 0xc1980000, v135
	v_add_f32_e32 v136, 0xc24c0000, v135
	v_mul_f32_e64 v134, v193, |v134|
	v_mul_f32_e64 v136, v193, |v136|
	v_fma_f32 v97, s101, v97, v134
	v_fma_f32 v81, s101, v81, v136
	v_add_f32_e32 v134, 0xc1c00000, v135
	v_add_f32_e32 v136, 0xc2600000, v135
	v_mul_f32_e64 v134, v193, |v134|
	v_mul_f32_e64 v136, v193, |v136|
	v_fma_f32 v98, s101, v98, v134
	v_fma_f32 v82, s101, v82, v136
	v_add_f32_e32 v134, 0xc1c80000, v135
	v_add_f32_e32 v136, 0xc2640000, v135
	v_mul_f32_e64 v134, v193, |v134|
	v_mul_f32_e64 v136, v193, |v136|
	v_fma_f32 v99, s101, v99, v134
	v_fma_f32 v83, s101, v83, v136
	v_add_f32_e32 v134, 0xc1d00000, v135
	v_add_f32_e32 v136, 0xc2680000, v135
	v_mul_f32_e64 v134, v193, |v134|
	v_mul_f32_e64 v136, v193, |v136|
	v_fma_f32 v100, s101, v100, v134
	v_fma_f32 v84, s101, v84, v136
	v_add_f32_e32 v134, 0xc1d80000, v135
	v_add_f32_e32 v136, 0xc26c0000, v135
	v_mul_f32_e64 v134, v193, |v134|
	v_mul_f32_e64 v136, v193, |v136|
	v_fma_f32 v101, s101, v101, v134
	v_fma_f32 v85, s101, v85, v136
	s_branch .Lam_done_1

.LBB0_568:
	v_add_u32_e32 v70, 0x100, v209
	s_movk_i32 s16, 0xfeff
	v_add_u32_e32 v72, 0x120, v209
	v_min_i32_e32 v70, s3, v70
	v_cmp_lt_i32_e32 vcc, s16, v209
	s_movk_i32 s16, 0xfedf
	v_min_i32_e32 v72, s3, v72
	v_cndmask_b32_e32 v70, 0, v70, vcc
	v_cmp_lt_i32_e32 vcc, s16, v209
	v_ashrrev_i32_e32 v71, 31, v70
	v_lshlrev_b64 v[70:71], s18, v[70:71]
	v_cndmask_b32_e32 v72, 0, v72, vcc
	v_ashrrev_i32_e32 v73, 31, v72
	v_lshlrev_b64 v[72:73], s18, v[72:73]
	v_lshl_add_u64 v[70:71], v[70:71], 0, v[2:3]
	v_lshl_add_u64 v[72:73], v[72:73], 0, v[2:3]
	v_lshlrev_b64 v[70:71], 1, v[70:71]
	v_lshlrev_b64 v[72:73], 1, v[72:73]
	v_lshl_add_u64 v[74:75], s[12:13], 0, v[70:71]
	v_lshl_add_u64 v[76:77], s[12:13], 0, v[72:73]
	v_lshl_add_u64 v[72:73], s[10:11], 0, v[72:73]
	s_waitcnt vmcnt(4)
	s_waitcnt vmcnt(7)
	ds_write_b128 v196, v[150:153]
	s_waitcnt vmcnt(6)
	ds_write_b128 v197, v[154:157]
	s_waitcnt vmcnt(4)
	ds_write_b128 v198, v[170:173] offset:32768
	ds_write_b128 v199, v[166:169] offset:32768
	s_waitcnt lgkmcnt(0)
	s_barrier
	global_load_dwordx4 v[134:137], v[74:75], off
	global_load_dwordx4 v[138:141], v[76:77], off
	v_lshl_add_u64 v[70:71], s[10:11], 0, v[70:71]
	global_load_dwordx4 v[150:153], v[72:73], off
	global_load_dwordx4 v[154:157], v[70:71], off
	s_cmp_gt_u32 s46, 2
	s_cbranch_scc1 .LBB0_574
	ds_read_b128 v[70:73], v207 offset:32768
	ds_read_b128 v[74:77], v207 offset:40960
	ds_read_b128 v[166:169], v206 offset:32768
	ds_read_b128 v[170:173], v206 offset:40960
	s_waitcnt lgkmcnt(3)
	v_mfma_f32_32x32x16_bf16 v[86:101], v[70:73], v[110:113], 0
	s_waitcnt lgkmcnt(2)
	v_mfma_f32_32x32x16_bf16 v[70:85], v[74:77], v[110:113], 0
	ds_read_b128 v[212:215], v205 offset:32768
	ds_read_b128 v[216:219], v205 offset:40960
	s_waitcnt lgkmcnt(3)
	v_mfma_f32_32x32x16_bf16 v[86:101], v[166:169], v[130:133], v[86:101]
	s_waitcnt lgkmcnt(2)
	v_mfma_f32_32x32x16_bf16 v[70:85], v[170:173], v[130:133], v[70:85]
	ds_read_b128 v[166:169], v204 offset:32768
	ds_read_b128 v[170:173], v204 offset:40960
	s_waitcnt lgkmcnt(3)
	v_mfma_f32_32x32x16_bf16 v[86:101], v[212:215], v[126:129], v[86:101]
	s_waitcnt lgkmcnt(2)
	v_mfma_f32_32x32x16_bf16 v[70:85], v[216:219], v[126:129], v[70:85]
	ds_read_b128 v[212:215], v203 offset:32768
	ds_read_b128 v[216:219], v203 offset:40960
	s_waitcnt lgkmcnt(3)
	v_mfma_f32_32x32x16_bf16 v[86:101], v[166:169], v[122:125], v[86:101]
	s_waitcnt lgkmcnt(2)
	v_mfma_f32_32x32x16_bf16 v[70:85], v[170:173], v[122:125], v[70:85]
	ds_read_b128 v[166:169], v202 offset:32768
	ds_read_b128 v[170:173], v202 offset:40960
	s_waitcnt lgkmcnt(3)
	v_mfma_f32_32x32x16_bf16 v[86:101], v[212:215], v[118:121], v[86:101]
	s_waitcnt lgkmcnt(2)
	v_mfma_f32_32x32x16_bf16 v[70:85], v[216:219], v[118:121], v[70:85]
	ds_read_b128 v[212:215], v201 offset:32768
	ds_read_b128 v[216:219], v201 offset:40960
	s_waitcnt lgkmcnt(3)
	v_mfma_f32_32x32x16_bf16 v[86:101], v[166:169], v[114:117], v[86:101]
	s_waitcnt lgkmcnt(2)
	v_mfma_f32_32x32x16_bf16 v[70:85], v[170:173], v[114:117], v[70:85]
	ds_read_b128 v[166:169], v200 offset:32768
	ds_read_b128 v[170:173], v200 offset:40960
	s_waitcnt lgkmcnt(3)
	v_mfma_f32_32x32x16_bf16 v[86:101], v[212:215], v[106:109], v[86:101]
	s_waitcnt lgkmcnt(2)
	v_mfma_f32_32x32x16_bf16 v[70:85], v[216:219], v[106:109], v[70:85]
	s_waitcnt lgkmcnt(1)
	v_mfma_f32_32x32x16_bf16 v[86:101], v[166:169], v[102:105], v[86:101]
	s_waitcnt lgkmcnt(0)
	v_mfma_f32_32x32x16_bf16 v[70:85], v[170:173], v[102:105], v[70:85]
	v_add_u32_e32 v166, 0x80, v194
	v_sub_u32_e32 v167, v192, v166
	v_readfirstlane_b32 s100, v167
	v_cvt_f32_i32_e32 v167, v167
	v_readfirstlane_b32 s40, v166
	s_add_i32 s41, s40, 64
	s_cmp_lt_i32 s40, 0
	s_cbranch_scc1 .Lam_out_2
	s_cmp_gt_i32 s41, s45
	s_cbranch_scc1 .Lam_out_2
	s_add_i32 s100, s100, 1
	s_cmp_lt_u32 s100, 35
	s_cbranch_scc1 .Lam_in_2
	v_mov_b32_e32 v166, v167
	v_add_f32_e32 v168, 0xc2000000, v167
	v_cmp_le_f32_e64 vcc, |v166|, s76
	v_cmp_le_f32_e64 s[16:17], |v168|, s76
	v_mul_f32_e64 v166, v193, |v166|
	v_mul_f32_e64 v168, v193, |v168|
	v_fmac_f32_e32 v166, 0x3e0293ee, v86
	v_fmac_f32_e32 v168, 0x3e0293ee, v70
	v_cndmask_b32_e32 v86, v234, v166, vcc
	v_cndmask_b32_e64 v70, v234, v168, s[16:17]
	v_add_f32_e32 v166, -1.0, v167
	v_add_f32_e32 v168, 0xc2040000, v167
	v_cmp_le_f32_e64 vcc, |v166|, s76
	v_cmp_le_f32_e64 s[16:17], |v168|, s76
	v_mul_f32_e64 v166, v193, |v166|
	v_mul_f32_e64 v168, v193, |v168|
	v_fmac_f32_e32 v166, 0x3e0293ee, v87
	v_fmac_f32_e32 v168, 0x3e0293ee, v71
	v_cndmask_b32_e32 v87, v234, v166, vcc
	v_cndmask_b32_e64 v71, v234, v168, s[16:17]
	v_add_f32_e32 v166, -2.0, v167
	v_add_f32_e32 v168, 0xc2080000, v167
	v_cmp_le_f32_e64 vcc, |v166|, s76
	v_cmp_le_f32_e64 s[16:17], |v168|, s76
	v_mul_f32_e64 v166, v193, |v166|
	v_mul_f32_e64 v168, v193, |v168|
	v_fmac_f32_e32 v166, 0x3e0293ee, v88
	v_fmac_f32_e32 v168, 0x3e0293ee, v72
	v_cndmask_b32_e32 v88, v234, v166, vcc
	v_cndmask_b32_e64 v72, v234, v168, s[16:17]
	v_add_f32_e32 v166, 0xc0400000, v167
	v_add_f32_e32 v168, 0xc20c0000, v167
	v_cmp_le_f32_e64 vcc, |v166|, s76
	v_cmp_le_f32_e64 s[16:17], |v168|, s76
	v_mul_f32_e64 v166, v193, |v166|
	v_mul_f32_e64 v168, v193, |v168|
	v_fmac_f32_e32 v166, 0x3e0293ee, v89
	v_fmac_f32_e32 v168, 0x3e0293ee, v73
	v_cndmask_b32_e32 v89, v234, v166, vcc
	v_cndmask_b32_e64 v73, v234, v168, s[16:17]
	v_add_f32_e32 v166, 0xc1000000, v167
	v_add_f32_e32 v168, 0xc2200000, v167
	v_cmp_le_f32_e64 vcc, |v166|, s76
	v_cmp_le_f32_e64 s[16:17], |v168|, s76
	v_mul_f32_e64 v166, v193, |v166|
	v_mul_f32_e64 v168, v193, |v168|
	v_fmac_f32_e32 v166, 0x3e0293ee, v90
	v_fmac_f32_e32 v168, 0x3e0293ee, v74
	v_cndmask_b32_e32 v90, v234, v166, vcc
	v_cndmask_b32_e64 v74, v234, v168, s[16:17]
	v_add_f32_e32 v166, 0xc1100000, v167
	v_add_f32_e32 v168, 0xc2240000, v167
	v_cmp_le_f32_e64 vcc, |v166|, s76
	v_cmp_le_f32_e64 s[16:17], |v168|, s76
	v_mul_f32_e64 v166, v193, |v166|
	v_mul_f32_e64 v168, v193, |v168|
	v_fmac_f32_e32 v166, 0x3e0293ee, v91
	v_fmac_f32_e32 v168, 0x3e0293ee, v75
	v_cndmask_b32_e32 v91, v234, v166, vcc
	v_cndmask_b32_e64 v75, v234, v168, s[16:17]
	v_add_f32_e32 v166, 0xc1200000, v167
	v_add_f32_e32 v168, 0xc2280000, v167
	v_cmp_le_f32_e64 vcc, |v166|, s76
	v_cmp_le_f32_e64 s[16:17], |v168|, s76
	v_mul_f32_e64 v166, v193, |v166|
	v_mul_f32_e64 v168, v193, |v168|
	v_fmac_f32_e32 v166, 0x3e0293ee, v92
	v_fmac_f32_e32 v168, 0x3e0293ee, v76
	v_cndmask_b32_e32 v92, v234, v166, vcc
	v_cndmask_b32_e64 v76, v234, v168, s[16:17]
	v_add_f32_e32 v166, 0xc1300000, v167
	v_add_f32_e32 v168, 0xc22c0000, v167
	v_cmp_le_f32_e64 vcc, |v166|, s76
	v_cmp_le_f32_e64 s[16:17], |v168|, s76
	v_mul_f32_e64 v166, v193, |v166|
	v_mul_f32_e64 v168, v193, |v168|
	v_fmac_f32_e32 v166, 0x3e0293ee, v93
	v_fmac_f32_e32 v168, 0x3e0293ee, v77
	v_cndmask_b32_e32 v93, v234, v166, vcc
	v_cndmask_b32_e64 v77, v234, v168, s[16:17]
	v_add_f32_e32 v166, 0xc1800000, v167
	v_add_f32_e32 v168, 0xc2400000, v167
	v_cmp_le_f32_e64 vcc, |v166|, s76
	v_cmp_le_f32_e64 s[16:17], |v168|, s76
	v_mul_f32_e64 v166, v193, |v166|
	v_mul_f32_e64 v168, v193, |v168|
	v_fmac_f32_e32 v166, 0x3e0293ee, v94
	v_fmac_f32_e32 v168, 0x3e0293ee, v78
	v_cndmask_b32_e32 v94, v234, v166, vcc
	v_cndmask_b32_e64 v78, v234, v168, s[16:17]
	v_add_f32_e32 v166, 0xc1880000, v167
	v_add_f32_e32 v168, 0xc2440000, v167
	v_cmp_le_f32_e64 vcc, |v166|, s76
	v_cmp_le_f32_e64 s[16:17], |v168|, s76
	v_mul_f32_e64 v166, v193, |v166|
	v_mul_f32_e64 v168, v193, |v168|
	v_fmac_f32_e32 v166, 0x3e0293ee, v95
	v_fmac_f32_e32 v168, 0x3e0293ee, v79
	v_cndmask_b32_e32 v95, v234, v166, vcc
	v_cndmask_b32_e64 v79, v234, v168, s[16:17]
	v_add_f32_e32 v166, 0xc1900000, v167
	v_add_f32_e32 v168, 0xc2480000, v167
	v_cmp_le_f32_e64 vcc, |v166|, s76
	v_cmp_le_f32_e64 s[16:17], |v168|, s76
	v_mul_f32_e64 v166, v193, |v166|
	v_mul_f32_e64 v168, v193, |v168|
	v_fmac_f32_e32 v166, 0x3e0293ee, v96
	v_fmac_f32_e32 v168, 0x3e0293ee, v80
	v_cndmask_b32_e32 v96, v234, v166, vcc
	v_cndmask_b32_e64 v80, v234, v168, s[16:17]
	v_add_f32_e32 v166, 0xc1980000, v167
	v_add_f32_e32 v168, 0xc24c0000, v167
	v_cmp_le_f32_e64 vcc, |v166|, s76
	v_cmp_le_f32_e64 s[16:17], |v168|, s76
	v_mul_f32_e64 v166, v193, |v166|
	v_mul_f32_e64 v168, v193, |v168|
	v_fmac_f32_e32 v166, 0x3e0293ee, v97
	v_fmac_f32_e32 v168, 0x3e0293ee, v81
	v_cndmask_b32_e32 v97, v234, v166, vcc
	v_cndmask_b32_e64 v81, v234, v168, s[16:17]
	v_add_f32_e32 v166, 0xc1c00000, v167
	v_add_f32_e32 v168, 0xc2600000, v167
	v_cmp_le_f32_e64 vcc, |v166|, s76
	v_cmp_le_f32_e64 s[16:17], |v168|, s76
	v_mul_f32_e64 v166, v193, |v166|
	v_mul_f32_e64 v168, v193, |v168|
	v_fmac_f32_e32 v166, 0x3e0293ee, v98
	v_fmac_f32_e32 v168, 0x3e0293ee, v82
	v_cndmask_b32_e32 v98, v234, v166, vcc
	v_cndmask_b32_e64 v82, v234, v168, s[16:17]
	v_add_f32_e32 v166, 0xc1c80000, v167
	v_add_f32_e32 v168, 0xc2640000, v167
	v_cmp_le_f32_e64 vcc, |v166|, s76
	v_cmp_le_f32_e64 s[16:17], |v168|, s76
	v_mul_f32_e64 v166, v193, |v166|
	v_mul_f32_e64 v168, v193, |v168|
	v_fmac_f32_e32 v166, 0x3e0293ee, v99
	v_fmac_f32_e32 v168, 0x3e0293ee, v83
	v_cndmask_b32_e32 v99, v234, v166, vcc
	v_cndmask_b32_e64 v83, v234, v168, s[16:17]
	v_add_f32_e32 v166, 0xc1d00000, v167
	v_add_f32_e32 v168, 0xc2680000, v167
	v_cmp_le_f32_e64 vcc, |v166|, s76
	v_cmp_le_f32_e64 s[16:17], |v168|, s76
	v_mul_f32_e64 v166, v193, |v166|
	v_mul_f32_e64 v168, v193, |v168|
	v_fmac_f32_e32 v166, 0x3e0293ee, v100
	v_fmac_f32_e32 v168, 0x3e0293ee, v84
	v_cndmask_b32_e32 v100, v234, v166, vcc
	v_cndmask_b32_e64 v84, v234, v168, s[16:17]
	v_add_f32_e32 v166, 0xc1d80000, v167
	v_add_f32_e32 v168, 0xc26c0000, v167
	v_cmp_le_f32_e64 vcc, |v166|, s76
	v_cmp_le_f32_e64 s[16:17], |v168|, s76
	v_mul_f32_e64 v166, v193, |v166|
	v_mul_f32_e64 v168, v193, |v168|
	v_fmac_f32_e32 v166, 0x3e0293ee, v101
	v_fmac_f32_e32 v168, 0x3e0293ee, v85
	v_cndmask_b32_e32 v101, v234, v166, vcc
	v_cndmask_b32_e64 v85, v234, v168, s[16:17]
	s_branch .Lam_done_2
.Lam_in_2:
	s_mov_b32 s101, 0x3e0293ee
	s_nop 3
	v_add_f32_e32 v168, 0xc2000000, v167
	v_mul_f32_e64 v166, v193, |v167|
	v_mul_f32_e64 v168, v193, |v168|
	v_fma_f32 v86, s101, v86, v166
	v_fma_f32 v70, s101, v70, v168
	v_add_f32_e32 v166, -1.0, v167
	v_add_f32_e32 v168, 0xc2040000, v167
	v_mul_f32_e64 v166, v193, |v166|
	v_mul_f32_e64 v168, v193, |v168|
	v_fma_f32 v87, s101, v87, v166
	v_fma_f32 v71, s101, v71, v168
	v_add_f32_e32 v166, -2.0, v167
	v_add_f32_e32 v168, 0xc2080000, v167
	v_mul_f32_e64 v166, v193, |v166|
	v_mul_f32_e64 v168, v193, |v168|
	v_fma_f32 v88, s101, v88, v166
	v_fma_f32 v72, s101, v72, v168
	v_add_f32_e32 v166, 0xc0400000, v167
	v_add_f32_e32 v168, 0xc20c0000, v167
	v_mul_f32_e64 v166, v193, |v166|
	v_mul_f32_e64 v168, v193, |v168|
	v_fma_f32 v89, s101, v89, v166
	v_fma_f32 v73, s101, v73, v168
	v_add_f32_e32 v166, 0xc1000000, v167
	v_add_f32_e32 v168, 0xc2200000, v167
	v_mul_f32_e64 v166, v193, |v166|
	v_mul_f32_e64 v168, v193, |v168|
	v_fma_f32 v90, s101, v90, v166
	v_fma_f32 v74, s101, v74, v168
	v_add_f32_e32 v166, 0xc1100000, v167
	v_add_f32_e32 v168, 0xc2240000, v167
	v_mul_f32_e64 v166, v193, |v166|
	v_mul_f32_e64 v168, v193, |v168|
	v_fma_f32 v91, s101, v91, v166
	v_fma_f32 v75, s101, v75, v168
	v_add_f32_e32 v166, 0xc1200000, v167
	v_add_f32_e32 v168, 0xc2280000, v167
	v_mul_f32_e64 v166, v193, |v166|
	v_mul_f32_e64 v168, v193, |v168|
	v_fma_f32 v92, s101, v92, v166
	v_fma_f32 v76, s101, v76, v168
	v_add_f32_e32 v166, 0xc1300000, v167
	v_add_f32_e32 v168, 0xc22c0000, v167
	v_mul_f32_e64 v166, v193, |v166|
	v_mul_f32_e64 v168, v193, |v168|
	v_fma_f32 v93, s101, v93, v166
	v_fma_f32 v77, s101, v77, v168
	v_add_f32_e32 v166, 0xc1800000, v167
	v_add_f32_e32 v168, 0xc2400000, v167
	v_mul_f32_e64 v166, v193, |v166|
	v_mul_f32_e64 v168, v193, |v168|
	v_fma_f32 v94, s101, v94, v166
	v_fma_f32 v78, s101, v78, v168
	v_add_f32_e32 v166, 0xc1880000, v167
	v_add_f32_e32 v168, 0xc2440000, v167
	v_mul_f32_e64 v166, v193, |v166|
	v_mul_f32_e64 v168, v193, |v168|
	v_fma_f32 v95, s101, v95, v166
	v_fma_f32 v79, s101, v79, v168
	v_add_f32_e32 v166, 0xc1900000, v167
	v_add_f32_e32 v168, 0xc2480000, v167
	v_mul_f32_e64 v166, v193, |v166|
	v_mul_f32_e64 v168, v193, |v168|
	v_fma_f32 v96, s101, v96, v166
	v_fma_f32 v80, s101, v80, v168
	v_add_f32_e32 v166, 0xc1980000, v167
	v_add_f32_e32 v168, 0xc24c0000, v167
	v_mul_f32_e64 v166, v193, |v166|
	v_mul_f32_e64 v168, v193, |v168|
	v_fma_f32 v97, s101, v97, v166
	v_fma_f32 v81, s101, v81, v168
	v_add_f32_e32 v166, 0xc1c00000, v167
	v_add_f32_e32 v168, 0xc2600000, v167
	v_mul_f32_e64 v166, v193, |v166|
	v_mul_f32_e64 v168, v193, |v168|
	v_fma_f32 v98, s101, v98, v166
	v_fma_f32 v82, s101, v82, v168
	v_add_f32_e32 v166, 0xc1c80000, v167
	v_add_f32_e32 v168, 0xc2640000, v167
	v_mul_f32_e64 v166, v193, |v166|
	v_mul_f32_e64 v168, v193, |v168|
	v_fma_f32 v99, s101, v99, v166
	v_fma_f32 v83, s101, v83, v168
	v_add_f32_e32 v166, 0xc1d00000, v167
	v_add_f32_e32 v168, 0xc2680000, v167
	v_mul_f32_e64 v166, v193, |v166|
	v_mul_f32_e64 v168, v193, |v168|
	v_fma_f32 v100, s101, v100, v166
	v_fma_f32 v84, s101, v84, v168
	v_add_f32_e32 v166, 0xc1d80000, v167
	v_add_f32_e32 v168, 0xc26c0000, v167
	v_mul_f32_e64 v166, v193, |v166|
	v_mul_f32_e64 v168, v193, |v168|
	v_fma_f32 v101, s101, v101, v166
	v_fma_f32 v85, s101, v85, v168
	s_branch .Lam_done_2

.LBB0_575:
	v_add_u32_e32 v70, 0x80, v210
	v_add_u32_e32 v72, 0xa0, v210
	s_movk_i32 s16, 0xff7f
	v_min_i32_e32 v70, s3, v70
	v_cmp_lt_i32_e32 vcc, s16, v210
	v_min_i32_e32 v72, s3, v72
	s_movk_i32 s3, 0xff5f
	v_cndmask_b32_e32 v70, 0, v70, vcc
	v_cmp_lt_i32_e32 vcc, s3, v210
	v_ashrrev_i32_e32 v71, 31, v70
	v_lshlrev_b64 v[70:71], s18, v[70:71]
	v_cndmask_b32_e32 v72, 0, v72, vcc
	v_ashrrev_i32_e32 v73, 31, v72
	v_lshlrev_b64 v[72:73], s18, v[72:73]
	v_lshl_add_u64 v[70:71], v[70:71], 0, v[2:3]
	v_lshl_add_u64 v[72:73], v[72:73], 0, v[2:3]
	v_lshlrev_b64 v[70:71], 1, v[70:71]
	v_lshlrev_b64 v[72:73], 1, v[72:73]
	v_lshl_add_u64 v[74:75], s[12:13], 0, v[70:71]
	v_lshl_add_u64 v[76:77], s[12:13], 0, v[72:73]
	v_lshl_add_u64 v[72:73], s[10:11], 0, v[72:73]
	s_waitcnt vmcnt(4)
	s_waitcnt vmcnt(7)
	ds_write_b128 v196, v[142:145] offset:16384
	s_waitcnt vmcnt(6)
	ds_write_b128 v197, v[146:149] offset:16384
	s_waitcnt vmcnt(4)
	ds_write_b128 v198, v[162:165] offset:49152
	ds_write_b128 v199, v[158:161] offset:49152
	s_waitcnt lgkmcnt(0)
	s_barrier
	global_load_dwordx4 v[142:145], v[74:75], off
	global_load_dwordx4 v[146:149], v[76:77], off
	v_lshl_add_u64 v[70:71], s[10:11], 0, v[70:71]
	global_load_dwordx4 v[166:169], v[72:73], off
	global_load_dwordx4 v[170:173], v[70:71], off
	s_cmp_gt_u32 s19, 2
	s_cbranch_scc1 .LBB0_581
	ds_read_b128 v[70:73], v207 offset:49152
	ds_read_b128 v[74:77], v207 offset:57344
	ds_read_b128 v[158:161], v206 offset:49152
	ds_read_b128 v[162:165], v206 offset:57344
	s_waitcnt lgkmcnt(3)
	v_mfma_f32_32x32x16_bf16 v[86:101], v[70:73], v[110:113], 0
	s_waitcnt lgkmcnt(2)
	v_mfma_f32_32x32x16_bf16 v[70:85], v[74:77], v[110:113], 0
	ds_read_b128 v[214:217], v205 offset:49152
	ds_read_b128 v[218:221], v205 offset:57344
	s_waitcnt lgkmcnt(3)
	v_mfma_f32_32x32x16_bf16 v[86:101], v[158:161], v[130:133], v[86:101]
	s_waitcnt lgkmcnt(2)
	v_mfma_f32_32x32x16_bf16 v[70:85], v[162:165], v[130:133], v[70:85]
	ds_read_b128 v[158:161], v204 offset:49152
	ds_read_b128 v[162:165], v204 offset:57344
	s_waitcnt lgkmcnt(3)
	v_mfma_f32_32x32x16_bf16 v[86:101], v[214:217], v[126:129], v[86:101]
	s_waitcnt lgkmcnt(2)
	v_mfma_f32_32x32x16_bf16 v[70:85], v[218:221], v[126:129], v[70:85]
	ds_read_b128 v[214:217], v203 offset:49152
	ds_read_b128 v[218:221], v203 offset:57344
	s_waitcnt lgkmcnt(3)
	v_mfma_f32_32x32x16_bf16 v[86:101], v[158:161], v[122:125], v[86:101]
	s_waitcnt lgkmcnt(2)
	v_mfma_f32_32x32x16_bf16 v[70:85], v[162:165], v[122:125], v[70:85]
	ds_read_b128 v[158:161], v202 offset:49152
	ds_read_b128 v[162:165], v202 offset:57344
	s_waitcnt lgkmcnt(3)
	v_mfma_f32_32x32x16_bf16 v[86:101], v[214:217], v[118:121], v[86:101]
	s_waitcnt lgkmcnt(2)
	v_mfma_f32_32x32x16_bf16 v[70:85], v[218:221], v[118:121], v[70:85]
	ds_read_b128 v[214:217], v201 offset:49152
	ds_read_b128 v[218:221], v201 offset:57344
	s_waitcnt lgkmcnt(3)
	v_mfma_f32_32x32x16_bf16 v[86:101], v[158:161], v[114:117], v[86:101]
	s_waitcnt lgkmcnt(2)
	v_mfma_f32_32x32x16_bf16 v[70:85], v[162:165], v[114:117], v[70:85]
	ds_read_b128 v[158:161], v200 offset:49152
	ds_read_b128 v[162:165], v200 offset:57344
	s_waitcnt lgkmcnt(3)
	v_mfma_f32_32x32x16_bf16 v[86:101], v[214:217], v[106:109], v[86:101]
	s_waitcnt lgkmcnt(2)
	v_mfma_f32_32x32x16_bf16 v[70:85], v[218:221], v[106:109], v[70:85]
	s_waitcnt lgkmcnt(1)
	v_mfma_f32_32x32x16_bf16 v[86:101], v[158:161], v[102:105], v[86:101]
	s_waitcnt lgkmcnt(0)
	v_mfma_f32_32x32x16_bf16 v[70:85], v[162:165], v[102:105], v[70:85]
	v_add_u32_e32 v158, 0xc0, v194
	v_sub_u32_e32 v159, v192, v158
	v_readfirstlane_b32 s100, v159
	v_cvt_f32_i32_e32 v159, v159
	v_readfirstlane_b32 s40, v158
	s_add_i32 s41, s40, 64
	s_cmp_lt_i32 s40, 0
	s_cbranch_scc1 .Lam_out_3
	s_cmp_gt_i32 s41, s45
	s_cbranch_scc1 .Lam_out_3
	s_add_i32 s100, s100, 1
	s_cmp_lt_u32 s100, 35
	s_cbranch_scc1 .Lam_in_3
	v_mov_b32_e32 v158, v159
	v_add_f32_e32 v160, 0xc2000000, v159
	v_cmp_le_f32_e64 vcc, |v158|, s76
	v_cmp_le_f32_e64 s[10:11], |v160|, s76
	v_mul_f32_e64 v158, v193, |v158|
	v_mul_f32_e64 v160, v193, |v160|
	v_fmac_f32_e32 v158, 0x3e0293ee, v86
	v_fmac_f32_e32 v160, 0x3e0293ee, v70
	v_cndmask_b32_e32 v86, v234, v158, vcc
	v_cndmask_b32_e64 v70, v234, v160, s[10:11]
	v_add_f32_e32 v158, -1.0, v159
	v_add_f32_e32 v160, 0xc2040000, v159
	v_cmp_le_f32_e64 vcc, |v158|, s76
	v_cmp_le_f32_e64 s[10:11], |v160|, s76
	v_mul_f32_e64 v158, v193, |v158|
	v_mul_f32_e64 v160, v193, |v160|
	v_fmac_f32_e32 v158, 0x3e0293ee, v87
	v_fmac_f32_e32 v160, 0x3e0293ee, v71
	v_cndmask_b32_e32 v87, v234, v158, vcc
	v_cndmask_b32_e64 v71, v234, v160, s[10:11]
	v_add_f32_e32 v158, -2.0, v159
	v_add_f32_e32 v160, 0xc2080000, v159
	v_cmp_le_f32_e64 vcc, |v158|, s76
	v_cmp_le_f32_e64 s[10:11], |v160|, s76
	v_mul_f32_e64 v158, v193, |v158|
	v_mul_f32_e64 v160, v193, |v160|
	v_fmac_f32_e32 v158, 0x3e0293ee, v88
	v_fmac_f32_e32 v160, 0x3e0293ee, v72
	v_cndmask_b32_e32 v88, v234, v158, vcc
	v_cndmask_b32_e64 v72, v234, v160, s[10:11]
	v_add_f32_e32 v158, 0xc0400000, v159
	v_add_f32_e32 v160, 0xc20c0000, v159
	v_cmp_le_f32_e64 vcc, |v158|, s76
	v_cmp_le_f32_e64 s[10:11], |v160|, s76
	v_mul_f32_e64 v158, v193, |v158|
	v_mul_f32_e64 v160, v193, |v160|
	v_fmac_f32_e32 v158, 0x3e0293ee, v89
	v_fmac_f32_e32 v160, 0x3e0293ee, v73
	v_cndmask_b32_e32 v89, v234, v158, vcc
	v_cndmask_b32_e64 v73, v234, v160, s[10:11]
	v_add_f32_e32 v158, 0xc1000000, v159
	v_add_f32_e32 v160, 0xc2200000, v159
	v_cmp_le_f32_e64 vcc, |v158|, s76
	v_cmp_le_f32_e64 s[10:11], |v160|, s76
	v_mul_f32_e64 v158, v193, |v158|
	v_mul_f32_e64 v160, v193, |v160|
	v_fmac_f32_e32 v158, 0x3e0293ee, v90
	v_fmac_f32_e32 v160, 0x3e0293ee, v74
	v_cndmask_b32_e32 v90, v234, v158, vcc
	v_cndmask_b32_e64 v74, v234, v160, s[10:11]
	v_add_f32_e32 v158, 0xc1100000, v159
	v_add_f32_e32 v160, 0xc2240000, v159
	v_cmp_le_f32_e64 vcc, |v158|, s76
	v_cmp_le_f32_e64 s[10:11], |v160|, s76
	v_mul_f32_e64 v158, v193, |v158|
	v_mul_f32_e64 v160, v193, |v160|
	v_fmac_f32_e32 v158, 0x3e0293ee, v91
	v_fmac_f32_e32 v160, 0x3e0293ee, v75
	v_cndmask_b32_e32 v91, v234, v158, vcc
	v_cndmask_b32_e64 v75, v234, v160, s[10:11]
	v_add_f32_e32 v158, 0xc1200000, v159
	v_add_f32_e32 v160, 0xc2280000, v159
	v_cmp_le_f32_e64 vcc, |v158|, s76
	v_cmp_le_f32_e64 s[10:11], |v160|, s76
	v_mul_f32_e64 v158, v193, |v158|
	v_mul_f32_e64 v160, v193, |v160|
	v_fmac_f32_e32 v158, 0x3e0293ee, v92
	v_fmac_f32_e32 v160, 0x3e0293ee, v76
	v_cndmask_b32_e32 v92, v234, v158, vcc
	v_cndmask_b32_e64 v76, v234, v160, s[10:11]
	v_add_f32_e32 v158, 0xc1300000, v159
	v_add_f32_e32 v160, 0xc22c0000, v159
	v_cmp_le_f32_e64 vcc, |v158|, s76
	v_cmp_le_f32_e64 s[10:11], |v160|, s76
	v_mul_f32_e64 v158, v193, |v158|
	v_mul_f32_e64 v160, v193, |v160|
	v_fmac_f32_e32 v158, 0x3e0293ee, v93
	v_fmac_f32_e32 v160, 0x3e0293ee, v77
	v_cndmask_b32_e32 v93, v234, v158, vcc
	v_cndmask_b32_e64 v77, v234, v160, s[10:11]
	v_add_f32_e32 v158, 0xc1800000, v159
	v_add_f32_e32 v160, 0xc2400000, v159
	v_cmp_le_f32_e64 vcc, |v158|, s76
	v_cmp_le_f32_e64 s[10:11], |v160|, s76
	v_mul_f32_e64 v158, v193, |v158|
	v_mul_f32_e64 v160, v193, |v160|
	v_fmac_f32_e32 v158, 0x3e0293ee, v94
	v_fmac_f32_e32 v160, 0x3e0293ee, v78
	v_cndmask_b32_e32 v94, v234, v158, vcc
	v_cndmask_b32_e64 v78, v234, v160, s[10:11]
	v_add_f32_e32 v158, 0xc1880000, v159
	v_add_f32_e32 v160, 0xc2440000, v159
	v_cmp_le_f32_e64 vcc, |v158|, s76
	v_cmp_le_f32_e64 s[10:11], |v160|, s76
	v_mul_f32_e64 v158, v193, |v158|
	v_mul_f32_e64 v160, v193, |v160|
	v_fmac_f32_e32 v158, 0x3e0293ee, v95
	v_fmac_f32_e32 v160, 0x3e0293ee, v79
	v_cndmask_b32_e32 v95, v234, v158, vcc
	v_cndmask_b32_e64 v79, v234, v160, s[10:11]
	v_add_f32_e32 v158, 0xc1900000, v159
	v_add_f32_e32 v160, 0xc2480000, v159
	v_cmp_le_f32_e64 vcc, |v158|, s76
	v_cmp_le_f32_e64 s[10:11], |v160|, s76
	v_mul_f32_e64 v158, v193, |v158|
	v_mul_f32_e64 v160, v193, |v160|
	v_fmac_f32_e32 v158, 0x3e0293ee, v96
	v_fmac_f32_e32 v160, 0x3e0293ee, v80
	v_cndmask_b32_e32 v96, v234, v158, vcc
	v_cndmask_b32_e64 v80, v234, v160, s[10:11]
	v_add_f32_e32 v158, 0xc1980000, v159
	v_add_f32_e32 v160, 0xc24c0000, v159
	v_cmp_le_f32_e64 vcc, |v158|, s76
	v_cmp_le_f32_e64 s[10:11], |v160|, s76
	v_mul_f32_e64 v158, v193, |v158|
	v_mul_f32_e64 v160, v193, |v160|
	v_fmac_f32_e32 v158, 0x3e0293ee, v97
	v_fmac_f32_e32 v160, 0x3e0293ee, v81
	v_cndmask_b32_e32 v97, v234, v158, vcc
	v_cndmask_b32_e64 v81, v234, v160, s[10:11]
	v_add_f32_e32 v158, 0xc1c00000, v159
	v_add_f32_e32 v160, 0xc2600000, v159
	v_cmp_le_f32_e64 vcc, |v158|, s76
	v_cmp_le_f32_e64 s[10:11], |v160|, s76
	v_mul_f32_e64 v158, v193, |v158|
	v_mul_f32_e64 v160, v193, |v160|
	v_fmac_f32_e32 v158, 0x3e0293ee, v98
	v_fmac_f32_e32 v160, 0x3e0293ee, v82
	v_cndmask_b32_e32 v98, v234, v158, vcc
	v_cndmask_b32_e64 v82, v234, v160, s[10:11]
	v_add_f32_e32 v158, 0xc1c80000, v159
	v_add_f32_e32 v160, 0xc2640000, v159
	v_cmp_le_f32_e64 vcc, |v158|, s76
	v_cmp_le_f32_e64 s[10:11], |v160|, s76
	v_mul_f32_e64 v158, v193, |v158|
	v_mul_f32_e64 v160, v193, |v160|
	v_fmac_f32_e32 v158, 0x3e0293ee, v99
	v_fmac_f32_e32 v160, 0x3e0293ee, v83
	v_cndmask_b32_e32 v99, v234, v158, vcc
	v_cndmask_b32_e64 v83, v234, v160, s[10:11]
	v_add_f32_e32 v158, 0xc1d00000, v159
	v_add_f32_e32 v160, 0xc2680000, v159
	v_cmp_le_f32_e64 vcc, |v158|, s76
	v_cmp_le_f32_e64 s[10:11], |v160|, s76
	v_mul_f32_e64 v158, v193, |v158|
	v_mul_f32_e64 v160, v193, |v160|
	v_fmac_f32_e32 v158, 0x3e0293ee, v100
	v_fmac_f32_e32 v160, 0x3e0293ee, v84
	v_cndmask_b32_e32 v100, v234, v158, vcc
	v_cndmask_b32_e64 v84, v234, v160, s[10:11]
	v_add_f32_e32 v158, 0xc1d80000, v159
	v_add_f32_e32 v160, 0xc26c0000, v159
	v_cmp_le_f32_e64 vcc, |v158|, s76
	v_cmp_le_f32_e64 s[10:11], |v160|, s76
	v_mul_f32_e64 v158, v193, |v158|
	v_mul_f32_e64 v160, v193, |v160|
	v_fmac_f32_e32 v158, 0x3e0293ee, v101
	v_fmac_f32_e32 v160, 0x3e0293ee, v85
	v_cndmask_b32_e32 v101, v234, v158, vcc
	v_cndmask_b32_e64 v85, v234, v160, s[10:11]
	s_branch .Lam_done_3
.Lam_in_3:
	s_mov_b32 s101, 0x3e0293ee
	s_nop 3
	v_add_f32_e32 v160, 0xc2000000, v159
	v_mul_f32_e64 v158, v193, |v159|
	v_mul_f32_e64 v160, v193, |v160|
	v_fma_f32 v86, s101, v86, v158
	v_fma_f32 v70, s101, v70, v160
	v_add_f32_e32 v158, -1.0, v159
	v_add_f32_e32 v160, 0xc2040000, v159
	v_mul_f32_e64 v158, v193, |v158|
	v_mul_f32_e64 v160, v193, |v160|
	v_fma_f32 v87, s101, v87, v158
	v_fma_f32 v71, s101, v71, v160
	v_add_f32_e32 v158, -2.0, v159
	v_add_f32_e32 v160, 0xc2080000, v159
	v_mul_f32_e64 v158, v193, |v158|
	v_mul_f32_e64 v160, v193, |v160|
	v_fma_f32 v88, s101, v88, v158
	v_fma_f32 v72, s101, v72, v160
	v_add_f32_e32 v158, 0xc0400000, v159
	v_add_f32_e32 v160, 0xc20c0000, v159
	v_mul_f32_e64 v158, v193, |v158|
	v_mul_f32_e64 v160, v193, |v160|
	v_fma_f32 v89, s101, v89, v158
	v_fma_f32 v73, s101, v73, v160
	v_add_f32_e32 v158, 0xc1000000, v159
	v_add_f32_e32 v160, 0xc2200000, v159
	v_mul_f32_e64 v158, v193, |v158|
	v_mul_f32_e64 v160, v193, |v160|
	v_fma_f32 v90, s101, v90, v158
	v_fma_f32 v74, s101, v74, v160
	v_add_f32_e32 v158, 0xc1100000, v159
	v_add_f32_e32 v160, 0xc2240000, v159
	v_mul_f32_e64 v158, v193, |v158|
	v_mul_f32_e64 v160, v193, |v160|
	v_fma_f32 v91, s101, v91, v158
	v_fma_f32 v75, s101, v75, v160
	v_add_f32_e32 v158, 0xc1200000, v159
	v_add_f32_e32 v160, 0xc2280000, v159
	v_mul_f32_e64 v158, v193, |v158|
	v_mul_f32_e64 v160, v193, |v160|
	v_fma_f32 v92, s101, v92, v158
	v_fma_f32 v76, s101, v76, v160
	v_add_f32_e32 v158, 0xc1300000, v159
	v_add_f32_e32 v160, 0xc22c0000, v159
	v_mul_f32_e64 v158, v193, |v158|
	v_mul_f32_e64 v160, v193, |v160|
	v_fma_f32 v93, s101, v93, v158
	v_fma_f32 v77, s101, v77, v160
	v_add_f32_e32 v158, 0xc1800000, v159
	v_add_f32_e32 v160, 0xc2400000, v159
	v_mul_f32_e64 v158, v193, |v158|
	v_mul_f32_e64 v160, v193, |v160|
	v_fma_f32 v94, s101, v94, v158
	v_fma_f32 v78, s101, v78, v160
	v_add_f32_e32 v158, 0xc1880000, v159
	v_add_f32_e32 v160, 0xc2440000, v159
	v_mul_f32_e64 v158, v193, |v158|
	v_mul_f32_e64 v160, v193, |v160|
	v_fma_f32 v95, s101, v95, v158
	v_fma_f32 v79, s101, v79, v160
	v_add_f32_e32 v158, 0xc1900000, v159
	v_add_f32_e32 v160, 0xc2480000, v159
	v_mul_f32_e64 v158, v193, |v158|
	v_mul_f32_e64 v160, v193, |v160|
	v_fma_f32 v96, s101, v96, v158
	v_fma_f32 v80, s101, v80, v160
	v_add_f32_e32 v158, 0xc1980000, v159
	v_add_f32_e32 v160, 0xc24c0000, v159
	v_mul_f32_e64 v158, v193, |v158|
	v_mul_f32_e64 v160, v193, |v160|
	v_fma_f32 v97, s101, v97, v158
	v_fma_f32 v81, s101, v81, v160
	v_add_f32_e32 v158, 0xc1c00000, v159
	v_add_f32_e32 v160, 0xc2600000, v159
	v_mul_f32_e64 v158, v193, |v158|
	v_mul_f32_e64 v160, v193, |v160|
	v_fma_f32 v98, s101, v98, v158
	v_fma_f32 v82, s101, v82, v160
	v_add_f32_e32 v158, 0xc1c80000, v159
	v_add_f32_e32 v160, 0xc2640000, v159
	v_mul_f32_e64 v158, v193, |v158|
	v_mul_f32_e64 v160, v193, |v160|
	v_fma_f32 v99, s101, v99, v158
	v_fma_f32 v83, s101, v83, v160
	v_add_f32_e32 v158, 0xc1d00000, v159
	v_add_f32_e32 v160, 0xc2680000, v159
	v_mul_f32_e64 v158, v193, |v158|
	v_mul_f32_e64 v160, v193, |v160|
	v_fma_f32 v100, s101, v100, v158
	v_fma_f32 v84, s101, v84, v160
	v_add_f32_e32 v158, 0xc1d80000, v159
	v_add_f32_e32 v160, 0xc26c0000, v159
	v_mul_f32_e64 v158, v193, |v158|
	v_mul_f32_e64 v160, v193, |v160|
	v_fma_f32 v101, s101, v101, v158
	v_fma_f32 v85, s101, v85, v160
	s_branch .Lam_done_3

.LBB0_582:
	v_readlane_b32 s3, v251, 2
	s_add_i32 s3, s3, s26
	s_cmpk_gt_i32 s3, 0x8ff
	s_cselect_b64 s[10:11], -1, 0
	s_cmpk_lt_i32 s3, 0x900
	s_cselect_b32 s12, s3, s26
	s_ashr_i32 s13, s12, 3
	s_andn2_b32 s13, s13, 31
	s_and_b32 s16, s12, 31
	s_or_b32 s13, s13, s16
	s_mul_hi_i32 s16, s13, 0x2aaaaaab
	s_lshr_b32 s17, s16, 31
	s_ashr_i32 s16, s16, 4
	s_add_i32 s16, s16, s17
	s_mul_i32 s17, s16, 0x60
	s_sub_i32 s13, s13, s17
	s_lshl_b32 s17, s13, 8
	s_add_i32 s17, s17, 0x7fffe000
	s_and_b32 s17, s17, 0x7ffff000
	s_addk_i32 s17, 0x2000
	s_and_b32 s18, s13, 15
	s_cmp_lt_i32 s13, 32
	s_movk_i32 s19, 0x1000
	s_cselect_b32 s17, 0, s17
	s_cselect_b32 s19, 0x2000, s19
	s_cselect_b32 s13, s13, s18
	s_lshl_b32 s16, s16, 1
	s_lshl_b32 s18, 1, s16
	v_cvt_f32_u32_e32 v70, s18
	s_sub_i32 s26, 0, s18
	s_ashr_i32 s22, s13, 31
	s_add_i32 s23, s13, s22
	v_rcp_iflag_f32_e32 v70, v70
	s_xor_b32 s23, s23, s22
	s_bfe_u32 s12, s12, 0x30005
	s_mul_i32 s12, s12, 0x600000
	v_mul_f32_e32 v70, 0x4f7ffffe, v70
	v_cvt_u32_f32_e32 v70, v70
	s_waitcnt vmcnt(4)
	s_waitcnt vmcnt(7)
	ds_write_b128 v196, v[134:137]
	s_waitcnt vmcnt(6)
	ds_write_b128 v197, v[138:141]
	s_waitcnt vmcnt(4)
	ds_write_b128 v198, v[154:157] offset:32768
	ds_write_b128 v199, v[150:153] offset:32768
	s_waitcnt lgkmcnt(0)
	v_readfirstlane_b32 s27, v70
	s_mul_i32 s26, s26, s27
	s_mul_hi_u32 s26, s27, s26
	s_add_i32 s27, s27, s26
	s_mul_hi_u32 s26, s23, s27
	s_mul_i32 s27, s26, s18
	s_sub_i32 s23, s23, s27
	s_sub_i32 s27, s23, s18
	s_add_i32 s40, s26, 1
	s_cmp_ge_u32 s23, s18
	s_cselect_b32 s26, s40, s26
	s_cselect_b32 s23, s27, s23
	s_add_i32 s27, s26, 1
	s_cmp_ge_u32 s23, s18
	s_cselect_b32 s23, s27, s26
	s_xor_b32 s23, s23, s22
	s_sub_i32 s22, s23, s22
	s_mul_i32 s18, s22, s18
	s_sub_i32 s13, s13, s18
	s_lshl_b32 s47, s22, 8
	s_lshr_b32 s51, s19, s16
	s_add_u32 s48, s70, s12
	s_addc_u32 s49, s71, 0
	s_add_i32 s22, s13, s17
	s_ashr_i32 s23, s22, 31
	s_lshl_b64 s[12:13], s[22:23], 8
	s_add_u32 s17, s48, s12
	s_addc_u32 s19, s49, s13
	s_add_u32 s12, s17, 0x3000000
	s_addc_u32 s13, s19, 0
	s_add_u32 s18, s17, 0x6000000
	s_addc_u32 s19, s19, 0
	s_sub_i32 s17, s47, 64
	v_add_u32_e32 v72, s17, v195
	s_add_i32 s51, s51, -1
	v_add_u32_e32 v73, 32, v72
	v_min_i32_e32 v70, s51, v72
	v_cmp_lt_i32_e32 vcc, -1, v72
	s_movk_i32 s17, 0xffdf
	v_min_i32_e32 v73, s51, v73
	v_cndmask_b32_e32 v70, 0, v70, vcc
	v_cmp_lt_i32_e32 vcc, s17, v72
	v_ashrrev_i32_e32 v71, 31, v70
	s_add_u32 s50, s16, 7
	v_cndmask_b32_e32 v72, 0, v73, vcc
	v_ashrrev_i32_e32 v73, 31, v72
	v_lshlrev_b64 v[70:71], s50, v[70:71]
	v_lshl_add_u64 v[70:71], v[2:3], 0, v[70:71]
	v_lshlrev_b64 v[72:73], s50, v[72:73]
	v_lshlrev_b64 v[70:71], 1, v[70:71]
	v_lshl_add_u64 v[72:73], v[2:3], 0, v[72:73]
	v_lshl_add_u64 v[74:75], s[18:19], 0, v[70:71]
	v_lshlrev_b64 v[72:73], 1, v[72:73]
	v_lshl_add_u64 v[76:77], s[18:19], 0, v[72:73]
	v_lshl_add_u64 v[70:71], s[12:13], 0, v[70:71]
	v_lshl_add_u64 v[72:73], s[12:13], 0, v[72:73]
	s_barrier
	global_load_dwordx4 v[162:165], v[74:75], off
	global_load_dwordx4 v[158:161], v[76:77], off
	global_load_dwordx4 v[154:157], v[70:71], off
	global_load_dwordx4 v[150:153], v[72:73], off
	s_add_i32 s16, s46, -5
	s_cmp_lt_u32 s16, -3
	s_cbranch_scc1 .LBB0_588
	ds_read_b128 v[70:73], v207 offset:32768
	ds_read_b128 v[74:77], v207 offset:40960
	ds_read_b128 v[134:137], v206 offset:32768
	ds_read_b128 v[138:141], v206 offset:40960
	s_waitcnt lgkmcnt(3)
	v_mfma_f32_32x32x16_bf16 v[86:101], v[70:73], v[110:113], 0
	s_waitcnt lgkmcnt(2)
	v_mfma_f32_32x32x16_bf16 v[70:85], v[74:77], v[110:113], 0
	ds_read_b128 v[210:213], v205 offset:32768
	ds_read_b128 v[214:217], v205 offset:40960
	s_waitcnt lgkmcnt(3)
	v_mfma_f32_32x32x16_bf16 v[86:101], v[134:137], v[130:133], v[86:101]
	s_waitcnt lgkmcnt(2)
	v_mfma_f32_32x32x16_bf16 v[70:85], v[138:141], v[130:133], v[70:85]
	ds_read_b128 v[134:137], v204 offset:32768
	ds_read_b128 v[138:141], v204 offset:40960
	s_waitcnt lgkmcnt(3)
	v_mfma_f32_32x32x16_bf16 v[86:101], v[210:213], v[126:129], v[86:101]
	s_waitcnt lgkmcnt(2)
	v_mfma_f32_32x32x16_bf16 v[70:85], v[214:217], v[126:129], v[70:85]
	ds_read_b128 v[210:213], v203 offset:32768
	ds_read_b128 v[214:217], v203 offset:40960
	s_waitcnt lgkmcnt(3)
	v_mfma_f32_32x32x16_bf16 v[86:101], v[134:137], v[122:125], v[86:101]
	s_waitcnt lgkmcnt(2)
	v_mfma_f32_32x32x16_bf16 v[70:85], v[138:141], v[122:125], v[70:85]
	ds_read_b128 v[134:137], v202 offset:32768
	ds_read_b128 v[138:141], v202 offset:40960
	s_waitcnt lgkmcnt(3)
	v_mfma_f32_32x32x16_bf16 v[86:101], v[210:213], v[118:121], v[86:101]
	s_waitcnt lgkmcnt(2)
	v_mfma_f32_32x32x16_bf16 v[70:85], v[214:217], v[118:121], v[70:85]
	ds_read_b128 v[210:213], v201 offset:32768
	ds_read_b128 v[214:217], v201 offset:40960
	s_waitcnt lgkmcnt(3)
	v_mfma_f32_32x32x16_bf16 v[86:101], v[134:137], v[114:117], v[86:101]
	s_waitcnt lgkmcnt(2)
	v_mfma_f32_32x32x16_bf16 v[70:85], v[138:141], v[114:117], v[70:85]
	ds_read_b128 v[134:137], v200 offset:32768
	ds_read_b128 v[138:141], v200 offset:40960
	s_waitcnt lgkmcnt(3)
	v_mfma_f32_32x32x16_bf16 v[86:101], v[210:213], v[106:109], v[86:101]
	s_waitcnt lgkmcnt(2)
	v_mfma_f32_32x32x16_bf16 v[70:85], v[214:217], v[106:109], v[70:85]
	s_waitcnt lgkmcnt(1)
	v_mfma_f32_32x32x16_bf16 v[86:101], v[134:137], v[102:105], v[86:101]
	s_waitcnt lgkmcnt(0)
	v_mfma_f32_32x32x16_bf16 v[70:85], v[138:141], v[102:105], v[70:85]
	v_add_u32_e32 v134, 0x100, v194
	v_sub_u32_e32 v135, v192, v134
	v_readfirstlane_b32 s100, v135
	v_cvt_f32_i32_e32 v135, v135
	v_readfirstlane_b32 s40, v134
	s_add_i32 s41, s40, 64
	s_cmp_lt_i32 s40, 0
	s_cbranch_scc1 .Lam_out_4
	s_cmp_gt_i32 s41, s45
	s_cbranch_scc1 .Lam_out_4
	s_add_i32 s100, s100, 1
	s_cmp_lt_u32 s100, 35
	s_cbranch_scc1 .Lam_in_4
	v_mov_b32_e32 v134, v135
	v_add_f32_e32 v136, 0xc2000000, v135
	v_cmp_le_f32_e64 vcc, |v134|, s76
	v_cmp_le_f32_e64 s[16:17], |v136|, s76
	v_mul_f32_e64 v134, v193, |v134|
	v_mul_f32_e64 v136, v193, |v136|
	v_fmac_f32_e32 v134, 0x3e0293ee, v86
	v_fmac_f32_e32 v136, 0x3e0293ee, v70
	v_cndmask_b32_e32 v86, v234, v134, vcc
	v_cndmask_b32_e64 v70, v234, v136, s[16:17]
	v_add_f32_e32 v134, -1.0, v135
	v_add_f32_e32 v136, 0xc2040000, v135
	v_cmp_le_f32_e64 vcc, |v134|, s76
	v_cmp_le_f32_e64 s[16:17], |v136|, s76
	v_mul_f32_e64 v134, v193, |v134|
	v_mul_f32_e64 v136, v193, |v136|
	v_fmac_f32_e32 v134, 0x3e0293ee, v87
	v_fmac_f32_e32 v136, 0x3e0293ee, v71
	v_cndmask_b32_e32 v87, v234, v134, vcc
	v_cndmask_b32_e64 v71, v234, v136, s[16:17]
	v_add_f32_e32 v134, -2.0, v135
	v_add_f32_e32 v136, 0xc2080000, v135
	v_cmp_le_f32_e64 vcc, |v134|, s76
	v_cmp_le_f32_e64 s[16:17], |v136|, s76
	v_mul_f32_e64 v134, v193, |v134|
	v_mul_f32_e64 v136, v193, |v136|
	v_fmac_f32_e32 v134, 0x3e0293ee, v88
	v_fmac_f32_e32 v136, 0x3e0293ee, v72
	v_cndmask_b32_e32 v88, v234, v134, vcc
	v_cndmask_b32_e64 v72, v234, v136, s[16:17]
	v_add_f32_e32 v134, 0xc0400000, v135
	v_add_f32_e32 v136, 0xc20c0000, v135
	v_cmp_le_f32_e64 vcc, |v134|, s76
	v_cmp_le_f32_e64 s[16:17], |v136|, s76
	v_mul_f32_e64 v134, v193, |v134|
	v_mul_f32_e64 v136, v193, |v136|
	v_fmac_f32_e32 v134, 0x3e0293ee, v89
	v_fmac_f32_e32 v136, 0x3e0293ee, v73
	v_cndmask_b32_e32 v89, v234, v134, vcc
	v_cndmask_b32_e64 v73, v234, v136, s[16:17]
	v_add_f32_e32 v134, 0xc1000000, v135
	v_add_f32_e32 v136, 0xc2200000, v135
	v_cmp_le_f32_e64 vcc, |v134|, s76
	v_cmp_le_f32_e64 s[16:17], |v136|, s76
	v_mul_f32_e64 v134, v193, |v134|
	v_mul_f32_e64 v136, v193, |v136|
	v_fmac_f32_e32 v134, 0x3e0293ee, v90
	v_fmac_f32_e32 v136, 0x3e0293ee, v74
	v_cndmask_b32_e32 v90, v234, v134, vcc
	v_cndmask_b32_e64 v74, v234, v136, s[16:17]
	v_add_f32_e32 v134, 0xc1100000, v135
	v_add_f32_e32 v136, 0xc2240000, v135
	v_cmp_le_f32_e64 vcc, |v134|, s76
	v_cmp_le_f32_e64 s[16:17], |v136|, s76
	v_mul_f32_e64 v134, v193, |v134|
	v_mul_f32_e64 v136, v193, |v136|
	v_fmac_f32_e32 v134, 0x3e0293ee, v91
	v_fmac_f32_e32 v136, 0x3e0293ee, v75
	v_cndmask_b32_e32 v91, v234, v134, vcc
	v_cndmask_b32_e64 v75, v234, v136, s[16:17]
	v_add_f32_e32 v134, 0xc1200000, v135
	v_add_f32_e32 v136, 0xc2280000, v135
	v_cmp_le_f32_e64 vcc, |v134|, s76
	v_cmp_le_f32_e64 s[16:17], |v136|, s76
	v_mul_f32_e64 v134, v193, |v134|
	v_mul_f32_e64 v136, v193, |v136|
	v_fmac_f32_e32 v134, 0x3e0293ee, v92
	v_fmac_f32_e32 v136, 0x3e0293ee, v76
	v_cndmask_b32_e32 v92, v234, v134, vcc
	v_cndmask_b32_e64 v76, v234, v136, s[16:17]
	v_add_f32_e32 v134, 0xc1300000, v135
	v_add_f32_e32 v136, 0xc22c0000, v135
	v_cmp_le_f32_e64 vcc, |v134|, s76
	v_cmp_le_f32_e64 s[16:17], |v136|, s76
	v_mul_f32_e64 v134, v193, |v134|
	v_mul_f32_e64 v136, v193, |v136|
	v_fmac_f32_e32 v134, 0x3e0293ee, v93
	v_fmac_f32_e32 v136, 0x3e0293ee, v77
	v_cndmask_b32_e32 v93, v234, v134, vcc
	v_cndmask_b32_e64 v77, v234, v136, s[16:17]
	v_add_f32_e32 v134, 0xc1800000, v135
	v_add_f32_e32 v136, 0xc2400000, v135
	v_cmp_le_f32_e64 vcc, |v134|, s76
	v_cmp_le_f32_e64 s[16:17], |v136|, s76
	v_mul_f32_e64 v134, v193, |v134|
	v_mul_f32_e64 v136, v193, |v136|
	v_fmac_f32_e32 v134, 0x3e0293ee, v94
	v_fmac_f32_e32 v136, 0x3e0293ee, v78
	v_cndmask_b32_e32 v94, v234, v134, vcc
	v_cndmask_b32_e64 v78, v234, v136, s[16:17]
	v_add_f32_e32 v134, 0xc1880000, v135
	v_add_f32_e32 v136, 0xc2440000, v135
	v_cmp_le_f32_e64 vcc, |v134|, s76
	v_cmp_le_f32_e64 s[16:17], |v136|, s76
	v_mul_f32_e64 v134, v193, |v134|
	v_mul_f32_e64 v136, v193, |v136|
	v_fmac_f32_e32 v134, 0x3e0293ee, v95
	v_fmac_f32_e32 v136, 0x3e0293ee, v79
	v_cndmask_b32_e32 v95, v234, v134, vcc
	v_cndmask_b32_e64 v79, v234, v136, s[16:17]
	v_add_f32_e32 v134, 0xc1900000, v135
	v_add_f32_e32 v136, 0xc2480000, v135
	v_cmp_le_f32_e64 vcc, |v134|, s76
	v_cmp_le_f32_e64 s[16:17], |v136|, s76
	v_mul_f32_e64 v134, v193, |v134|
	v_mul_f32_e64 v136, v193, |v136|
	v_fmac_f32_e32 v134, 0x3e0293ee, v96
	v_fmac_f32_e32 v136, 0x3e0293ee, v80
	v_cndmask_b32_e32 v96, v234, v134, vcc
	v_cndmask_b32_e64 v80, v234, v136, s[16:17]
	v_add_f32_e32 v134, 0xc1980000, v135
	v_add_f32_e32 v136, 0xc24c0000, v135
	v_cmp_le_f32_e64 vcc, |v134|, s76
	v_cmp_le_f32_e64 s[16:17], |v136|, s76
	v_mul_f32_e64 v134, v193, |v134|
	v_mul_f32_e64 v136, v193, |v136|
	v_fmac_f32_e32 v134, 0x3e0293ee, v97
	v_fmac_f32_e32 v136, 0x3e0293ee, v81
	v_cndmask_b32_e32 v97, v234, v134, vcc
	v_cndmask_b32_e64 v81, v234, v136, s[16:17]
	v_add_f32_e32 v134, 0xc1c00000, v135
	v_add_f32_e32 v136, 0xc2600000, v135
	v_cmp_le_f32_e64 vcc, |v134|, s76
	v_cmp_le_f32_e64 s[16:17], |v136|, s76
	v_mul_f32_e64 v134, v193, |v134|
	v_mul_f32_e64 v136, v193, |v136|
	v_fmac_f32_e32 v134, 0x3e0293ee, v98
	v_fmac_f32_e32 v136, 0x3e0293ee, v82
	v_cndmask_b32_e32 v98, v234, v134, vcc
	v_cndmask_b32_e64 v82, v234, v136, s[16:17]
	v_add_f32_e32 v134, 0xc1c80000, v135
	v_add_f32_e32 v136, 0xc2640000, v135
	v_cmp_le_f32_e64 vcc, |v134|, s76
	v_cmp_le_f32_e64 s[16:17], |v136|, s76
	v_mul_f32_e64 v134, v193, |v134|
	v_mul_f32_e64 v136, v193, |v136|
	v_fmac_f32_e32 v134, 0x3e0293ee, v99
	v_fmac_f32_e32 v136, 0x3e0293ee, v83
	v_cndmask_b32_e32 v99, v234, v134, vcc
	v_cndmask_b32_e64 v83, v234, v136, s[16:17]
	v_add_f32_e32 v134, 0xc1d00000, v135
	v_add_f32_e32 v136, 0xc2680000, v135
	v_cmp_le_f32_e64 vcc, |v134|, s76
	v_cmp_le_f32_e64 s[16:17], |v136|, s76
	v_mul_f32_e64 v134, v193, |v134|
	v_mul_f32_e64 v136, v193, |v136|
	v_fmac_f32_e32 v134, 0x3e0293ee, v100
	v_fmac_f32_e32 v136, 0x3e0293ee, v84
	v_cndmask_b32_e32 v100, v234, v134, vcc
	v_cndmask_b32_e64 v84, v234, v136, s[16:17]
	v_add_f32_e32 v134, 0xc1d80000, v135
	v_add_f32_e32 v136, 0xc26c0000, v135
	v_cmp_le_f32_e64 vcc, |v134|, s76
	v_cmp_le_f32_e64 s[16:17], |v136|, s76
	v_mul_f32_e64 v134, v193, |v134|
	v_mul_f32_e64 v136, v193, |v136|
	v_fmac_f32_e32 v134, 0x3e0293ee, v101
	v_fmac_f32_e32 v136, 0x3e0293ee, v85
	v_cndmask_b32_e32 v101, v234, v134, vcc
	v_cndmask_b32_e64 v85, v234, v136, s[16:17]
	s_branch .Lam_done_4

.LBB0_589:
	v_add_u32_e32 v72, s47, v195
	v_add_u32_e32 v73, 32, v72
	v_min_i32_e32 v70, s51, v72
	v_cmp_lt_i32_e32 vcc, -1, v72
	s_movk_i32 s16, 0xffdf
	v_min_i32_e32 v73, s51, v73
	v_cndmask_b32_e32 v70, 0, v70, vcc
	v_cmp_lt_i32_e32 vcc, s16, v72
	v_ashrrev_i32_e32 v71, 31, v70
	v_lshlrev_b64 v[70:71], s50, v[70:71]
	v_cndmask_b32_e32 v72, 0, v73, vcc
	v_ashrrev_i32_e32 v73, 31, v72
	v_lshl_add_u64 v[70:71], v[2:3], 0, v[70:71]
	v_lshlrev_b64 v[72:73], s50, v[72:73]
	v_lshlrev_b64 v[70:71], 1, v[70:71]
	v_lshl_add_u64 v[72:73], v[2:3], 0, v[72:73]
	v_lshl_add_u64 v[74:75], s[18:19], 0, v[70:71]
	v_lshlrev_b64 v[72:73], 1, v[72:73]
	v_lshl_add_u64 v[76:77], s[18:19], 0, v[72:73]
	v_lshl_add_u64 v[70:71], s[12:13], 0, v[70:71]
	v_lshl_add_u64 v[72:73], s[12:13], 0, v[72:73]
	s_waitcnt vmcnt(4)
	s_waitcnt vmcnt(7)
	ds_write_b128 v196, v[142:145] offset:16384
	s_waitcnt vmcnt(6)
	ds_write_b128 v197, v[146:149] offset:16384
	s_waitcnt vmcnt(4)
	ds_write_b128 v198, v[170:173] offset:49152
	ds_write_b128 v199, v[166:169] offset:49152
	s_waitcnt lgkmcnt(0)
	s_barrier
	global_load_dwordx4 v[134:137], v[74:75], off
	global_load_dwordx4 v[138:141], v[76:77], off
	global_load_dwordx4 v[142:145], v[70:71], off
	global_load_dwordx4 v[146:149], v[72:73], off
	s_lshl_b64 s[22:23], s[22:23], 7
	s_add_i32 s46, s46, -3
	s_cmp_gt_u32 s46, 2
	s_cbranch_scc1 .LBB0_595
	ds_read_b128 v[70:73], v207 offset:49152
	ds_read_b128 v[74:77], v207 offset:57344
	ds_read_b128 v[166:169], v206 offset:49152
	ds_read_b128 v[170:173], v206 offset:57344
	s_waitcnt lgkmcnt(3)
	v_mfma_f32_32x32x16_bf16 v[86:101], v[70:73], v[110:113], 0
	s_waitcnt lgkmcnt(2)
	v_mfma_f32_32x32x16_bf16 v[70:85], v[74:77], v[110:113], 0
	ds_read_b128 v[110:113], v205 offset:49152
	ds_read_b128 v[196:199], v205 offset:57344
	s_waitcnt lgkmcnt(3)
	v_mfma_f32_32x32x16_bf16 v[86:101], v[166:169], v[130:133], v[86:101]
	s_waitcnt lgkmcnt(2)
	v_mfma_f32_32x32x16_bf16 v[70:85], v[170:173], v[130:133], v[70:85]
	ds_read_b128 v[130:133], v204 offset:49152
	ds_read_b128 v[166:169], v204 offset:57344
	s_waitcnt lgkmcnt(3)
	v_mfma_f32_32x32x16_bf16 v[86:101], v[110:113], v[126:129], v[86:101]
	s_waitcnt lgkmcnt(2)
	v_mfma_f32_32x32x16_bf16 v[70:85], v[196:199], v[126:129], v[70:85]
	ds_read_b128 v[110:113], v203 offset:49152
	ds_read_b128 v[126:129], v203 offset:57344
	s_waitcnt lgkmcnt(3)
	v_mfma_f32_32x32x16_bf16 v[86:101], v[130:133], v[122:125], v[86:101]
	s_waitcnt lgkmcnt(2)
	v_mfma_f32_32x32x16_bf16 v[70:85], v[166:169], v[122:125], v[70:85]
	ds_read_b128 v[122:125], v202 offset:49152
	ds_read_b128 v[130:133], v202 offset:57344
	s_waitcnt lgkmcnt(3)
	v_mfma_f32_32x32x16_bf16 v[86:101], v[110:113], v[118:121], v[86:101]
	s_waitcnt lgkmcnt(2)
	v_mfma_f32_32x32x16_bf16 v[70:85], v[126:129], v[118:121], v[70:85]
	ds_read_b128 v[110:113], v201 offset:49152
	ds_read_b128 v[118:121], v201 offset:57344
	s_waitcnt lgkmcnt(3)
	v_mfma_f32_32x32x16_bf16 v[86:101], v[122:125], v[114:117], v[86:101]
	s_waitcnt lgkmcnt(2)
	v_mfma_f32_32x32x16_bf16 v[70:85], v[130:133], v[114:117], v[70:85]
	ds_read_b128 v[114:117], v200 offset:49152
	ds_read_b128 v[122:125], v200 offset:57344
	s_waitcnt lgkmcnt(3)
	v_mfma_f32_32x32x16_bf16 v[86:101], v[110:113], v[106:109], v[86:101]
	s_waitcnt lgkmcnt(2)
	v_mfma_f32_32x32x16_bf16 v[70:85], v[118:121], v[106:109], v[70:85]
	s_waitcnt lgkmcnt(1)
	v_mfma_f32_32x32x16_bf16 v[86:101], v[114:117], v[102:105], v[86:101]
	s_waitcnt lgkmcnt(0)
	v_mfma_f32_32x32x16_bf16 v[70:85], v[122:125], v[102:105], v[70:85]
	v_add_u32_e32 v102, 0x140, v194
	v_sub_u32_e32 v103, v192, v102
	v_readfirstlane_b32 s100, v103
	v_cvt_f32_i32_e32 v103, v103
	v_readfirstlane_b32 s40, v102
	s_add_i32 s41, s40, 64
	s_cmp_lt_i32 s40, 0
	s_cbranch_scc1 .Lam_out_5
	s_cmp_gt_i32 s41, s45
	s_cbranch_scc1 .Lam_out_5
	s_add_i32 s100, s100, 1
	s_cmp_lt_u32 s100, 35
	s_cbranch_scc1 .Lam_in_5
	v_add_f32_e32 v104, 0xc2000000, v103
	v_mov_b32_e32 v105, v103
	v_cmp_le_f32_e64 vcc, |v104|, s76
	v_cmp_le_f32_e64 s[12:13], |v105|, s76
	v_mul_f32_e64 v104, v193, |v104|
	v_mul_f32_e64 v105, v193, |v105|
	v_fmac_f32_e32 v104, 0x3e0293ee, v70
	v_fmac_f32_e32 v105, 0x3e0293ee, v86
	v_cndmask_b32_e32 v70, v234, v104, vcc
	v_cndmask_b32_e64 v102, v234, v105, s[12:13]
	v_add_f32_e32 v104, -1.0, v103
	v_add_f32_e32 v105, 0xc2040000, v103
	v_cmp_le_f32_e64 vcc, |v104|, s76
	v_cmp_le_f32_e64 s[12:13], |v105|, s76
	v_mul_f32_e64 v104, v193, |v104|
	v_mul_f32_e64 v105, v193, |v105|
	v_fmac_f32_e32 v104, 0x3e0293ee, v87
	v_fmac_f32_e32 v105, 0x3e0293ee, v71
	v_cndmask_b32_e32 v87, v234, v104, vcc
	v_cndmask_b32_e64 v71, v234, v105, s[12:13]
	v_add_f32_e32 v104, -2.0, v103
	v_add_f32_e32 v105, 0xc2080000, v103
	v_cmp_le_f32_e64 vcc, |v104|, s76
	v_cmp_le_f32_e64 s[12:13], |v105|, s76
	v_mul_f32_e64 v104, v193, |v104|
	v_mul_f32_e64 v105, v193, |v105|
	v_fmac_f32_e32 v104, 0x3e0293ee, v88
	v_fmac_f32_e32 v105, 0x3e0293ee, v72
	v_cndmask_b32_e32 v88, v234, v104, vcc
	v_cndmask_b32_e64 v72, v234, v105, s[12:13]
	v_add_f32_e32 v104, 0xc0400000, v103
	v_add_f32_e32 v105, 0xc20c0000, v103
	v_cmp_le_f32_e64 vcc, |v104|, s76
	v_cmp_le_f32_e64 s[12:13], |v105|, s76
	v_mul_f32_e64 v104, v193, |v104|
	v_mul_f32_e64 v105, v193, |v105|
	v_fmac_f32_e32 v104, 0x3e0293ee, v89
	v_fmac_f32_e32 v105, 0x3e0293ee, v73
	v_cndmask_b32_e32 v89, v234, v104, vcc
	v_cndmask_b32_e64 v73, v234, v105, s[12:13]
	v_add_f32_e32 v104, 0xc1000000, v103
	v_add_f32_e32 v105, 0xc2200000, v103
	v_cmp_le_f32_e64 vcc, |v104|, s76
	v_cmp_le_f32_e64 s[12:13], |v105|, s76
	v_mul_f32_e64 v104, v193, |v104|
	v_mul_f32_e64 v105, v193, |v105|
	v_fmac_f32_e32 v104, 0x3e0293ee, v90
	v_fmac_f32_e32 v105, 0x3e0293ee, v74
	v_cndmask_b32_e32 v90, v234, v104, vcc
	v_cndmask_b32_e64 v74, v234, v105, s[12:13]
	v_add_f32_e32 v104, 0xc1100000, v103
	v_add_f32_e32 v105, 0xc2240000, v103
	v_cmp_le_f32_e64 vcc, |v104|, s76
	v_cmp_le_f32_e64 s[12:13], |v105|, s76
	v_mul_f32_e64 v104, v193, |v104|
	v_mul_f32_e64 v105, v193, |v105|
	v_fmac_f32_e32 v104, 0x3e0293ee, v91
	v_fmac_f32_e32 v105, 0x3e0293ee, v75
	v_cndmask_b32_e32 v91, v234, v104, vcc
	v_cndmask_b32_e64 v75, v234, v105, s[12:13]
	v_add_f32_e32 v104, 0xc1200000, v103
	v_add_f32_e32 v105, 0xc2280000, v103
	v_cmp_le_f32_e64 vcc, |v104|, s76
	v_cmp_le_f32_e64 s[12:13], |v105|, s76
	v_mul_f32_e64 v104, v193, |v104|
	v_mul_f32_e64 v105, v193, |v105|
	v_fmac_f32_e32 v104, 0x3e0293ee, v92
	v_fmac_f32_e32 v105, 0x3e0293ee, v76
	v_cndmask_b32_e32 v92, v234, v104, vcc
	v_cndmask_b32_e64 v76, v234, v105, s[12:13]
	v_add_f32_e32 v104, 0xc1300000, v103
	v_add_f32_e32 v105, 0xc22c0000, v103
	v_cmp_le_f32_e64 vcc, |v104|, s76
	v_cmp_le_f32_e64 s[12:13], |v105|, s76
	v_mul_f32_e64 v104, v193, |v104|
	v_mul_f32_e64 v105, v193, |v105|
	v_fmac_f32_e32 v104, 0x3e0293ee, v93
	v_fmac_f32_e32 v105, 0x3e0293ee, v77
	v_cndmask_b32_e32 v93, v234, v104, vcc
	v_cndmask_b32_e64 v77, v234, v105, s[12:13]
	v_add_f32_e32 v104, 0xc1800000, v103
	v_add_f32_e32 v105, 0xc2400000, v103
	v_cmp_le_f32_e64 vcc, |v104|, s76
	v_cmp_le_f32_e64 s[12:13], |v105|, s76
	v_mul_f32_e64 v104, v193, |v104|
	v_mul_f32_e64 v105, v193, |v105|
	v_fmac_f32_e32 v104, 0x3e0293ee, v94
	v_fmac_f32_e32 v105, 0x3e0293ee, v78
	v_cndmask_b32_e32 v94, v234, v104, vcc
	v_cndmask_b32_e64 v78, v234, v105, s[12:13]
	v_add_f32_e32 v104, 0xc1880000, v103
	v_add_f32_e32 v105, 0xc2440000, v103
	v_cmp_le_f32_e64 vcc, |v104|, s76
	v_cmp_le_f32_e64 s[12:13], |v105|, s76
	v_mul_f32_e64 v104, v193, |v104|
	v_mul_f32_e64 v105, v193, |v105|
	v_fmac_f32_e32 v104, 0x3e0293ee, v95
	v_fmac_f32_e32 v105, 0x3e0293ee, v79
	v_cndmask_b32_e32 v95, v234, v104, vcc
	v_cndmask_b32_e64 v79, v234, v105, s[12:13]
	v_add_f32_e32 v104, 0xc1900000, v103
	v_add_f32_e32 v105, 0xc2480000, v103
	v_cmp_le_f32_e64 vcc, |v104|, s76
	v_cmp_le_f32_e64 s[12:13], |v105|, s76
	v_mul_f32_e64 v104, v193, |v104|
	v_mul_f32_e64 v105, v193, |v105|
	v_fmac_f32_e32 v104, 0x3e0293ee, v96
	v_fmac_f32_e32 v105, 0x3e0293ee, v80
	v_cndmask_b32_e32 v96, v234, v104, vcc
	v_cndmask_b32_e64 v80, v234, v105, s[12:13]
	v_add_f32_e32 v104, 0xc1980000, v103
	v_add_f32_e32 v105, 0xc24c0000, v103
	v_cmp_le_f32_e64 vcc, |v104|, s76
	v_cmp_le_f32_e64 s[12:13], |v105|, s76
	v_mul_f32_e64 v104, v193, |v104|
	v_mul_f32_e64 v105, v193, |v105|
	v_fmac_f32_e32 v104, 0x3e0293ee, v97
	v_fmac_f32_e32 v105, 0x3e0293ee, v81
	v_cndmask_b32_e32 v97, v234, v104, vcc
	v_cndmask_b32_e64 v81, v234, v105, s[12:13]
	v_add_f32_e32 v104, 0xc1c00000, v103
	v_add_f32_e32 v105, 0xc2600000, v103
	v_cmp_le_f32_e64 vcc, |v104|, s76
	v_cmp_le_f32_e64 s[12:13], |v105|, s76
	v_mul_f32_e64 v104, v193, |v104|
	v_mul_f32_e64 v105, v193, |v105|
	v_fmac_f32_e32 v104, 0x3e0293ee, v98
	v_fmac_f32_e32 v105, 0x3e0293ee, v82
	v_cndmask_b32_e32 v98, v234, v104, vcc
	v_cndmask_b32_e64 v82, v234, v105, s[12:13]
	v_add_f32_e32 v104, 0xc1c80000, v103
	v_add_f32_e32 v105, 0xc2640000, v103
	v_cmp_le_f32_e64 vcc, |v104|, s76
	v_cmp_le_f32_e64 s[12:13], |v105|, s76
	v_mul_f32_e64 v104, v193, |v104|
	v_mul_f32_e64 v105, v193, |v105|
	v_fmac_f32_e32 v104, 0x3e0293ee, v99
	v_fmac_f32_e32 v105, 0x3e0293ee, v83
	v_cndmask_b32_e32 v99, v234, v104, vcc
	v_cndmask_b32_e64 v83, v234, v105, s[12:13]
	v_add_f32_e32 v104, 0xc1d00000, v103
	v_add_f32_e32 v105, 0xc2680000, v103
	v_cmp_le_f32_e64 vcc, |v104|, s76
	v_cmp_le_f32_e64 s[12:13], |v105|, s76
	v_mul_f32_e64 v104, v193, |v104|
	v_mul_f32_e64 v105, v193, |v105|
	v_fmac_f32_e32 v104, 0x3e0293ee, v100
	v_fmac_f32_e32 v105, 0x3e0293ee, v84
	v_cndmask_b32_e32 v100, v234, v104, vcc
	v_cndmask_b32_e64 v84, v234, v105, s[12:13]
	v_add_f32_e32 v104, 0xc1d80000, v103
	v_add_f32_e32 v105, 0xc26c0000, v103
	v_cmp_le_f32_e64 vcc, |v104|, s76
	v_cmp_le_f32_e64 s[12:13], |v105|, s76
	v_mul_f32_e64 v104, v193, |v104|
	v_mul_f32_e64 v105, v193, |v105|
	v_fmac_f32_e32 v104, 0x3e0293ee, v101
	v_fmac_f32_e32 v105, 0x3e0293ee, v85
	v_cndmask_b32_e32 v101, v234, v104, vcc
	v_cndmask_b32_e64 v85, v234, v105, s[12:13]
	s_branch .Lam_done_5
.Lam_in_5:
	s_mov_b32 s101, 0x3e0293ee
	s_nop 3
	v_add_f32_e32 v104, 0xc2000000, v103
	v_mul_f32_e64 v104, v193, |v104|
	v_mul_f32_e64 v105, v193, |v103|
	v_fma_f32 v70, s101, v70, v104
	v_fma_f32 v102, s101, v86, v105
	v_add_f32_e32 v104, -1.0, v103
	v_add_f32_e32 v105, 0xc2040000, v103
	v_mul_f32_e64 v104, v193, |v104|
	v_mul_f32_e64 v105, v193, |v105|
	v_fma_f32 v87, s101, v87, v104
	v_fma_f32 v71, s101, v71, v105
	v_add_f32_e32 v104, -2.0, v103
	v_add_f32_e32 v105, 0xc2080000, v103
	v_mul_f32_e64 v104, v193, |v104|
	v_mul_f32_e64 v105, v193, |v105|
	v_fma_f32 v88, s101, v88, v104
	v_fma_f32 v72, s101, v72, v105
	v_add_f32_e32 v104, 0xc0400000, v103
	v_add_f32_e32 v105, 0xc20c0000, v103
	v_mul_f32_e64 v104, v193, |v104|
	v_mul_f32_e64 v105, v193, |v105|
	v_fma_f32 v89, s101, v89, v104
	v_fma_f32 v73, s101, v73, v105
	v_add_f32_e32 v104, 0xc1000000, v103
	v_add_f32_e32 v105, 0xc2200000, v103
	v_mul_f32_e64 v104, v193, |v104|
	v_mul_f32_e64 v105, v193, |v105|
	v_fma_f32 v90, s101, v90, v104
	v_fma_f32 v74, s101, v74, v105
	v_add_f32_e32 v104, 0xc1100000, v103
	v_add_f32_e32 v105, 0xc2240000, v103
	v_mul_f32_e64 v104, v193, |v104|
	v_mul_f32_e64 v105, v193, |v105|
	v_fma_f32 v91, s101, v91, v104
	v_fma_f32 v75, s101, v75, v105
	v_add_f32_e32 v104, 0xc1200000, v103
	v_add_f32_e32 v105, 0xc2280000, v103
	v_mul_f32_e64 v104, v193, |v104|
	v_mul_f32_e64 v105, v193, |v105|
	v_fma_f32 v92, s101, v92, v104
	v_fma_f32 v76, s101, v76, v105
	v_add_f32_e32 v104, 0xc1300000, v103
	v_add_f32_e32 v105, 0xc22c0000, v103
	v_mul_f32_e64 v104, v193, |v104|
	v_mul_f32_e64 v105, v193, |v105|
	v_fma_f32 v93, s101, v93, v104
	v_fma_f32 v77, s101, v77, v105
	v_add_f32_e32 v104, 0xc1800000, v103
	v_add_f32_e32 v105, 0xc2400000, v103
	v_mul_f32_e64 v104, v193, |v104|
	v_mul_f32_e64 v105, v193, |v105|
	v_fma_f32 v94, s101, v94, v104
	v_fma_f32 v78, s101, v78, v105
	v_add_f32_e32 v104, 0xc1880000, v103
	v_add_f32_e32 v105, 0xc2440000, v103
	v_mul_f32_e64 v104, v193, |v104|
	v_mul_f32_e64 v105, v193, |v105|
	v_fma_f32 v95, s101, v95, v104
	v_fma_f32 v79, s101, v79, v105
	v_add_f32_e32 v104, 0xc1900000, v103
	v_add_f32_e32 v105, 0xc2480000, v103
	v_mul_f32_e64 v104, v193, |v104|
	v_mul_f32_e64 v105, v193, |v105|
	v_fma_f32 v96, s101, v96, v104
	v_fma_f32 v80, s101, v80, v105
	v_add_f32_e32 v104, 0xc1980000, v103
	v_add_f32_e32 v105, 0xc24c0000, v103
	v_mul_f32_e64 v104, v193, |v104|
	v_mul_f32_e64 v105, v193, |v105|
	v_fma_f32 v97, s101, v97, v104
	v_fma_f32 v81, s101, v81, v105
	v_add_f32_e32 v104, 0xc1c00000, v103
	v_add_f32_e32 v105, 0xc2600000, v103
	v_mul_f32_e64 v104, v193, |v104|
	v_mul_f32_e64 v105, v193, |v105|
	v_fma_f32 v98, s101, v98, v104
	v_fma_f32 v82, s101, v82, v105
	v_add_f32_e32 v104, 0xc1c80000, v103
	v_add_f32_e32 v105, 0xc2640000, v103
	v_mul_f32_e64 v104, v193, |v104|
	v_mul_f32_e64 v105, v193, |v105|
	v_fma_f32 v99, s101, v99, v104
	v_fma_f32 v83, s101, v83, v105
	v_add_f32_e32 v104, 0xc1d00000, v103
	v_add_f32_e32 v105, 0xc2680000, v103
	v_mul_f32_e64 v104, v193, |v104|
	v_mul_f32_e64 v105, v193, |v105|
	v_fma_f32 v100, s101, v100, v104
	v_fma_f32 v84, s101, v84, v105
	v_add_f32_e32 v104, 0xc1d80000, v103
	v_add_f32_e32 v105, 0xc26c0000, v103
	v_mul_f32_e64 v104, v193, |v104|
	v_mul_f32_e64 v105, v193, |v105|
	v_fma_f32 v101, s101, v101, v104
	v_fma_f32 v85, s101, v85, v105
	s_branch .Lam_done_5
